# E32: E31 + in-proj QK-norm/rope epilogue reduction steps xor16/xor32 via v_permlane16_swap/v_permlane32_swap instead of ds_bpermute (bit-identical)
# baseline (speedup 1.0000x reference)
;     __device__ __forceinline__ void operator()(const f32x4 (&acc)[2][2][4][2], const Unit& u, int wr, int wc, int fr, int fq) const {
;     ...
;                     if (nrm) {
;                         float ss = 0.f;
; #pragma unroll
;                         for (int bj = 0; bj < 2; ++bj)
; #pragma unroll
;                             for (int n = 0; n < 2; ++n) ss += v[bj][n][0] * v[bj][n][0] + v[bj][n][1] * v[bj][n][1] + v[bj][n][2] * v[bj][n][2] + v[bj][n][3] * v[bj][n][3];
;                         ss += __shfl_xor(ss, 16); ss += __shfl_xor(ss, 32);
;                         const float rinv = __builtin_amdgcn_rsqf(ss * (1.f / 64.f) + EPS);
; #pragma unroll
;                         for (int bj = 0; bj < 2; ++bj)
; #pragma unroll
;                             for (int n = 0; n < 2; ++n) { const f32x4 x = v[bj][n] * wv[bj][n] * rinv; const f32x4 cs = *(const f32x4*)(CS + ((size_t)row * 32 + 16 * bj + 4 * fq + 2 * n) * 2);
;                                 f32x4 o; o[0] = x[0] * cs[0] - x[1] * cs[1]; o[1] = x[0] * cs[1] + x[1] * cs[0]; o[2] = x[2] * cs[2] - x[3] * cs[3]; o[3] = x[2] * cs[3] + x[3] * cs[2]; v[bj][n] = o * sc; }
.LBB0_270:
	s_and_b64 vcc, exec, s[4:5]
	s_cbranch_vccz .LBB0_295
	s_cmp_lt_u32 s16, 15
	v_readlane_b32 s4, v255, 58
	s_cselect_b64 vcc, -1, 0
	v_readlane_b32 s5, v255, 59
	s_or_b64 s[56:57], vcc, s[4:5]
	s_and_b64 s[4:5], vcc, exec
	s_cselect_b32 s4, s12, s14
	s_cselect_b32 s5, s13, s15
	s_add_u32 s4, s4, s38
	v_lshlrev_b32_e32 v178, 3, v173
	s_addc_u32 s5, s5, s39
	v_ashrrev_i32_e32 v179, 31, v178
	v_lshl_add_u64 v[132:133], v[178:179], 2, s[4:5]
	global_load_dwordx4 v[136:139], v[132:133], off offset:16
	global_load_dwordx4 v[140:143], v[132:133], off
	global_load_dwordx4 v[128:131], v[132:133], off offset:144
	s_nop 0
	global_load_dwordx4 v[132:135], v[132:133], off offset:128
	v_cndmask_b32_e64 v144, 0, 1, s[56:57]
	v_cndmask_b32_e32 v176, 1.0, v233, vcc
	v_lshlrev_b32_e32 v182, 2, v173
	v_cmp_ne_u32_e64 s[4:5], 1, v144
	v_mov_b64_e32 v[154:155], v[98:99]
	v_mov_b64_e32 v[158:159], v[122:123]
	v_mov_b64_e32 v[150:151], v[90:91]
	v_mov_b64_e32 v[146:147], v[126:127]
	v_ashrrev_i32_e32 v183, 31, v182
	v_mov_b32_e32 v177, v176
	v_ashrrev_i32_e32 v181, 31, v180
	s_andn2_b64 vcc, exec, s[56:57]
	v_mov_b64_e32 v[152:153], v[96:97]
	v_mov_b64_e32 v[156:157], v[120:121]
	v_mov_b64_e32 v[148:149], v[88:89]
	v_mov_b64_e32 v[144:145], v[124:125]
	s_cbranch_vccnz .LBB0_273
	v_mov_b32_e32 v146, v125
	v_mov_b32_e32 v147, v89
	v_mov_b32_e32 v144, v124
	v_mov_b32_e32 v145, v88
	v_pk_mul_f32 v[146:147], v[146:147], v[146:147]
	v_mov_b32_e32 v148, v121
	v_pk_fma_f32 v[144:145], v[144:145], v[144:145], v[146:147]
	v_mov_b32_e32 v146, v126
	v_mov_b32_e32 v147, v90
	v_pk_fma_f32 v[144:145], v[146:147], v[146:147], v[144:145]
	v_mov_b32_e32 v146, v127
	v_mov_b32_e32 v147, v91
	v_mov_b32_e32 v149, v97
	v_pk_fma_f32 v[144:145], v[146:147], v[146:147], v[144:145]
	v_mov_b32_e32 v146, v120
	v_mov_b32_e32 v147, v96
	v_pk_mul_f32 v[148:149], v[148:149], v[148:149]
	v_add_f32_e32 v144, v144, v145
	v_pk_fma_f32 v[146:147], v[146:147], v[146:147], v[148:149]
	v_mov_b32_e32 v148, v122
	v_mov_b32_e32 v149, v98
	v_pk_fma_f32 v[146:147], v[148:149], v[148:149], v[146:147]
	v_mov_b32_e32 v148, v123
	v_mov_b32_e32 v149, v99
	v_pk_fma_f32 v[146:147], v[148:149], v[148:149], v[146:147]
	v_mov_b32_e32 v186, v176
	v_add_f32_e32 v144, v144, v146
	v_add_f32_e32 v144, v144, v147
	v_mov_b32_e32 v145, v144
	s_nop 1
	v_permlane16_swap_b32_e32 v144, v145
	s_waitcnt vmcnt(0)
	v_pk_mul_f32 v[146:147], v[124:125], v[140:141]
	v_mov_b32_e32 v187, v176
	s_waitcnt lgkmcnt(0)
	v_add_f32_e32 v144, v144, v145
	v_mov_b32_e32 v145, v144
	s_nop 1
	v_permlane32_swap_b32_e32 v144, v145
	s_waitcnt lgkmcnt(0)
	v_add_f32_e32 v144, v144, v145
	v_fmamk_f32 v144, v144, 0x3c800000, v253
	v_rsq_f32_e32 v184, v144
	v_pk_mul_f32 v[144:145], v[126:127], v[142:143]
	v_pk_mul_f32 v[154:155], v[146:147], v[184:185] op_sel_hi:[1,0]
	v_pk_mul_f32 v[152:153], v[144:145], v[184:185] op_sel_hi:[1,0]
	v_lshlrev_b64 v[144:145], 8, v[180:181]
	v_lshl_add_u64 v[144:145], s[22:23], 0, v[144:145]
	v_lshl_add_u64 v[156:157], v[182:183], 3, v[144:145]
	global_load_dwordx4 v[148:151], v[156:157], off offset:16
	global_load_dwordx4 v[144:147], v[156:157], off
	global_load_dwordx4 v[240:243], v[156:157], off offset:144
	global_load_dwordx4 v[244:247], v[156:157], off offset:128
	s_waitcnt vmcnt(0)
	v_pk_mul_f32 v[158:159], v[144:145], v[154:155] op_sel:[1,1] op_sel_hi:[0,1]
	v_pk_fma_f32 v[190:191], v[144:145], v[154:155], v[158:159] op_sel_hi:[1,0,1] neg_lo:[0,0,1] neg_hi:[0,0,1]
	v_pk_fma_f32 v[144:145], v[144:145], v[154:155], v[158:159] op_sel_hi:[1,0,1]
	v_pk_mul_f32 v[154:155], v[146:147], v[152:153] op_sel:[1,1] op_sel_hi:[0,1]
	v_pk_fma_f32 v[158:159], v[146:147], v[152:153], v[154:155] op_sel_hi:[1,0,1] neg_lo:[0,0,1] neg_hi:[0,0,1]
	v_pk_fma_f32 v[146:147], v[146:147], v[152:153], v[154:155] op_sel_hi:[1,0,1]
	v_pk_mul_f32 v[154:155], v[88:89], v[136:137]
	v_mov_b32_e32 v159, v147
	v_pk_mul_f32 v[152:153], v[90:91], v[138:139]
	v_pk_mul_f32 v[154:155], v[154:155], v[184:185] op_sel_hi:[1,0]
	v_pk_mul_f32 v[146:147], v[186:187], v[158:159]
	v_mov_b32_e32 v191, v145
	v_pk_mul_f32 v[152:153], v[152:153], v[184:185] op_sel_hi:[1,0]
	v_pk_mul_f32 v[158:159], v[148:149], v[154:155] op_sel:[1,1] op_sel_hi:[0,1]
	v_pk_mul_f32 v[144:145], v[176:177], v[190:191]
	v_pk_fma_f32 v[190:191], v[148:149], v[154:155], v[158:159] op_sel_hi:[1,0,1] neg_lo:[0,0,1] neg_hi:[0,0,1]
	v_pk_fma_f32 v[148:149], v[148:149], v[154:155], v[158:159] op_sel_hi:[1,0,1]
	v_pk_mul_f32 v[154:155], v[150:151], v[152:153] op_sel:[1,1] op_sel_hi:[0,1]
	v_pk_fma_f32 v[158:159], v[150:151], v[152:153], v[154:155] op_sel_hi:[1,0,1] neg_lo:[0,0,1] neg_hi:[0,0,1]
	v_pk_fma_f32 v[150:151], v[150:151], v[152:153], v[154:155] op_sel_hi:[1,0,1]
	v_mov_b32_e32 v191, v149
	v_mov_b32_e32 v159, v151
	v_pk_mul_f32 v[152:153], v[122:123], v[134:135]
	v_pk_mul_f32 v[154:155], v[120:121], v[132:133]
	v_pk_mul_f32 v[150:151], v[186:187], v[158:159]
	v_pk_mul_f32 v[148:149], v[176:177], v[190:191]
	v_pk_mul_f32 v[190:191], v[152:153], v[184:185] op_sel_hi:[1,0]
	v_pk_mul_f32 v[200:201], v[154:155], v[184:185] op_sel_hi:[1,0]
	v_mov_b64_e32 v[152:153], v[240:241]
	v_mov_b64_e32 v[154:155], v[242:243]
	v_mov_b64_e32 v[156:157], v[244:245]
	v_mov_b64_e32 v[158:159], v[246:247]
	v_pk_mul_f32 v[202:203], v[156:157], v[200:201] op_sel:[1,1] op_sel_hi:[0,1]
	v_pk_fma_f32 v[204:205], v[156:157], v[200:201], v[202:203] op_sel_hi:[1,0,1] neg_lo:[0,0,1] neg_hi:[0,0,1]
	v_pk_fma_f32 v[156:157], v[156:157], v[200:201], v[202:203] op_sel_hi:[1,0,1]
	v_pk_mul_f32 v[200:201], v[158:159], v[190:191] op_sel:[1,1] op_sel_hi:[0,1]
	v_pk_fma_f32 v[202:203], v[158:159], v[190:191], v[200:201] op_sel_hi:[1,0,1] neg_lo:[0,0,1] neg_hi:[0,0,1]
	v_pk_fma_f32 v[158:159], v[158:159], v[190:191], v[200:201] op_sel_hi:[1,0,1]
	v_pk_mul_f32 v[190:191], v[98:99], v[130:131]
	v_pk_mul_f32 v[200:201], v[96:97], v[128:129]
	v_pk_mul_f32 v[190:191], v[190:191], v[184:185] op_sel_hi:[1,0]
	v_pk_mul_f32 v[184:185], v[200:201], v[184:185] op_sel_hi:[1,0]
	v_mov_b32_e32 v203, v159
	v_pk_mul_f32 v[200:201], v[152:153], v[184:185] op_sel:[1,1] op_sel_hi:[0,1]
	v_pk_mul_f32 v[158:159], v[186:187], v[202:203]
	v_pk_fma_f32 v[202:203], v[152:153], v[184:185], v[200:201] op_sel_hi:[1,0,1] neg_lo:[0,0,1] neg_hi:[0,0,1]
	v_pk_fma_f32 v[152:153], v[152:153], v[184:185], v[200:201] op_sel_hi:[1,0,1]
	v_pk_mul_f32 v[184:185], v[154:155], v[190:191] op_sel:[1,1] op_sel_hi:[0,1]
	v_pk_fma_f32 v[200:201], v[154:155], v[190:191], v[184:185] op_sel_hi:[1,0,1] neg_lo:[0,0,1] neg_hi:[0,0,1]
	v_pk_fma_f32 v[154:155], v[154:155], v[190:191], v[184:185] op_sel_hi:[1,0,1]
	v_mov_b32_e32 v205, v157
	v_mov_b32_e32 v201, v155
	v_mov_b32_e32 v203, v153
	v_pk_mul_f32 v[156:157], v[176:177], v[204:205]
	v_pk_mul_f32 v[154:155], v[186:187], v[200:201]
	v_pk_mul_f32 v[152:153], v[176:177], v[202:203]
; __device__ __forceinline__ unsigned cvt_pk_bf16(float lo, float hi) { f32x2_c v = {lo, hi}; bf16x2_c b = __builtin_convertvector(v, bf16x2_c); return __builtin_bit_cast(unsigned, b); }
;     __device__ __forceinline__ void operator()(const f32x4 (&acc)[2][2][4][2], const Unit& u, int wr, int wc, int fr, int fq) const {
;     ...
;                 for (int m = 0; m < 4; ++m) { const int row = row0 + ai * HALF + m * 16; bf16_t* rowp = PROJ + (size_t)row * PP + pn * 256 + 64 * wc + 8 * fq;
;                     f32x4 v[2][2];
; #pragma unroll
;                     for (int bj = 0; bj < 2; ++bj)
; #pragma unroll
;                         for (int n = 0; n < 2; ++n) v[bj][n] = acc[ai][bj][m][n];
;                     if (nrm) {
;                         float ss = 0.f;
; #pragma unroll
;                         for (int bj = 0; bj < 2; ++bj)
; #pragma unroll
;                             for (int n = 0; n < 2; ++n) ss += v[bj][n][0] * v[bj][n][0] + v[bj][n][1] * v[bj][n][1] + v[bj][n][2] * v[bj][n][2] + v[bj][n][3] * v[bj][n][3];
;                         ss += __shfl_xor(ss, 16); ss += __shfl_xor(ss, 32);
;                         const float rinv = __builtin_amdgcn_rsqf(ss * (1.f / 64.f) + EPS);
; #pragma unroll
;                         for (int bj = 0; bj < 2; ++bj)
; #pragma unroll
;                             for (int n = 0; n < 2; ++n) { const f32x4 x = v[bj][n] * wv[bj][n] * rinv; const f32x4 cs = *(const f32x4*)(CS + ((size_t)row * 32 + 16 * bj + 4 * fq + 2 * n) * 2);
;                                 f32x4 o; o[0] = x[0] * cs[0] - x[1] * cs[1]; o[1] = x[0] * cs[1] + x[1] * cs[0]; o[2] = x[2] * cs[2] - x[3] * cs[3]; o[3] = x[2] * cs[3] + x[3] * cs[2]; v[bj][n] = o * sc; }
;                     }
; #pragma unroll
;                     for (int bj = 0; bj < 2; ++bj) { u32x4 w; w.x = cvt_pk_bf16(v[bj][0][0], v[bj][0][1]); w.y = cvt_pk_bf16(v[bj][0][2], v[bj][0][3]); w.z = cvt_pk_bf16(v[bj][1][0], v[bj][1][1]); w.w = cvt_pk_bf16(v[bj][1][2], v[bj][1][3]);
;                         *(u32x4*)(rowp + 32 * bj) = w; } }
.LBB0_273:
	v_mov_b64_e32 v[184:185], s[24:25]
	v_mad_i64_i32 v[184:185], s[56:57], v180, s64, v[184:185]
	s_lshl_b32 s78, s16, 9
	v_lshl_add_u64 v[184:185], v[184:185], 0, s[78:79]
	s_lshl_b32 s78, s81, 1
	v_lshl_add_u64 v[184:185], v[184:185], 0, s[78:79]
	v_lshl_add_u64 v[184:185], v[178:179], 1, v[184:185]
	v_cvt_pk_bf16_f32 v144, v144, v145
	v_cvt_pk_bf16_f32 v145, v146, v147
	v_cvt_pk_bf16_f32 v146, v148, v149
	v_cvt_pk_bf16_f32 v147, v150, v151
	global_store_dwordx4 v[184:185], v[144:147], off
	v_mov_b64_e32 v[150:151], v[82:83]
	s_and_b64 vcc, exec, s[4:5]
	v_cvt_pk_bf16_f32 v144, v156, v157
	v_cvt_pk_bf16_f32 v145, v158, v159
	v_cvt_pk_bf16_f32 v146, v152, v153
	v_cvt_pk_bf16_f32 v147, v154, v155
	global_store_dwordx4 v[184:185], v[144:147], off offset:64
	v_add_u32_e32 v184, 16, v180
	v_mov_b64_e32 v[154:155], v[86:87]
	v_mov_b64_e32 v[158:159], v[114:115]
	v_mov_b64_e32 v[146:147], v[118:119]
	v_ashrrev_i32_e32 v185, 31, v184
	v_mov_b64_e32 v[152:153], v[84:85]
	v_mov_b64_e32 v[156:157], v[112:113]
	v_mov_b64_e32 v[148:149], v[80:81]
	v_mov_b64_e32 v[144:145], v[116:117]
	s_cbranch_vccnz .LBB0_275
	v_mov_b32_e32 v146, v117
	v_mov_b32_e32 v147, v81
	v_mov_b32_e32 v144, v116
	v_mov_b32_e32 v145, v80
	v_pk_mul_f32 v[146:147], v[146:147], v[146:147]
	v_mov_b32_e32 v148, v113
	v_pk_fma_f32 v[144:145], v[144:145], v[144:145], v[146:147]
	v_mov_b32_e32 v146, v118
	v_mov_b32_e32 v147, v82
	v_pk_fma_f32 v[144:145], v[146:147], v[146:147], v[144:145]
	v_mov_b32_e32 v146, v119
	v_mov_b32_e32 v147, v83
	v_mov_b32_e32 v149, v85
	v_pk_fma_f32 v[144:145], v[146:147], v[146:147], v[144:145]
	v_mov_b32_e32 v146, v112
	v_mov_b32_e32 v147, v84
	v_pk_mul_f32 v[148:149], v[148:149], v[148:149]
	v_add_f32_e32 v144, v144, v145
	v_pk_fma_f32 v[146:147], v[146:147], v[146:147], v[148:149]
	v_mov_b32_e32 v148, v114
	v_mov_b32_e32 v149, v86
	v_pk_fma_f32 v[146:147], v[148:149], v[148:149], v[146:147]
	v_mov_b32_e32 v148, v115
	v_mov_b32_e32 v149, v87
	v_pk_fma_f32 v[146:147], v[148:149], v[148:149], v[146:147]
	v_mov_b32_e32 v190, v176
	v_add_f32_e32 v144, v144, v146
	v_add_f32_e32 v144, v144, v147
	v_mov_b32_e32 v145, v144
	s_nop 1
	v_permlane16_swap_b32_e32 v144, v145
	v_pk_mul_f32 v[146:147], v[116:117], v[140:141]
	v_mov_b32_e32 v191, v176
	s_waitcnt lgkmcnt(0)
	v_add_f32_e32 v144, v144, v145
	v_mov_b32_e32 v145, v144
	s_nop 1
	v_permlane32_swap_b32_e32 v144, v145
	s_waitcnt lgkmcnt(0)
	v_add_f32_e32 v144, v144, v145
	v_fmamk_f32 v144, v144, 0x3c800000, v253
	v_rsq_f32_e32 v186, v144
	v_pk_mul_f32 v[144:145], v[118:119], v[142:143]
	v_pk_mul_f32 v[154:155], v[146:147], v[186:187] op_sel_hi:[1,0]
	v_pk_mul_f32 v[152:153], v[144:145], v[186:187] op_sel_hi:[1,0]
	v_lshlrev_b64 v[144:145], 8, v[184:185]
	v_lshl_add_u64 v[144:145], s[22:23], 0, v[144:145]
	v_lshl_add_u64 v[156:157], v[182:183], 3, v[144:145]
	global_load_dwordx4 v[148:151], v[156:157], off offset:16
	global_load_dwordx4 v[144:147], v[156:157], off
	global_load_dwordx4 v[240:243], v[156:157], off offset:144
	global_load_dwordx4 v[244:247], v[156:157], off offset:128
	s_waitcnt vmcnt(0)
	v_pk_mul_f32 v[158:159], v[144:145], v[154:155] op_sel:[1,1] op_sel_hi:[0,1]
	v_pk_fma_f32 v[200:201], v[144:145], v[154:155], v[158:159] op_sel_hi:[1,0,1] neg_lo:[0,0,1] neg_hi:[0,0,1]
	v_pk_fma_f32 v[144:145], v[144:145], v[154:155], v[158:159] op_sel_hi:[1,0,1]
	v_pk_mul_f32 v[154:155], v[146:147], v[152:153] op_sel:[1,1] op_sel_hi:[0,1]
	v_pk_fma_f32 v[158:159], v[146:147], v[152:153], v[154:155] op_sel_hi:[1,0,1] neg_lo:[0,0,1] neg_hi:[0,0,1]
	v_pk_fma_f32 v[146:147], v[146:147], v[152:153], v[154:155] op_sel_hi:[1,0,1]
	v_pk_mul_f32 v[154:155], v[80:81], v[136:137]
	v_mov_b32_e32 v159, v147
	v_pk_mul_f32 v[152:153], v[82:83], v[138:139]
	v_pk_mul_f32 v[154:155], v[154:155], v[186:187] op_sel_hi:[1,0]
	v_pk_mul_f32 v[146:147], v[190:191], v[158:159]
	v_mov_b32_e32 v201, v145
	v_pk_mul_f32 v[152:153], v[152:153], v[186:187] op_sel_hi:[1,0]
	v_pk_mul_f32 v[158:159], v[148:149], v[154:155] op_sel:[1,1] op_sel_hi:[0,1]
	v_pk_mul_f32 v[144:145], v[176:177], v[200:201]
	v_pk_fma_f32 v[200:201], v[148:149], v[154:155], v[158:159] op_sel_hi:[1,0,1] neg_lo:[0,0,1] neg_hi:[0,0,1]
	v_pk_fma_f32 v[148:149], v[148:149], v[154:155], v[158:159] op_sel_hi:[1,0,1]
	v_pk_mul_f32 v[154:155], v[150:151], v[152:153] op_sel:[1,1] op_sel_hi:[0,1]
	v_pk_fma_f32 v[158:159], v[150:151], v[152:153], v[154:155] op_sel_hi:[1,0,1] neg_lo:[0,0,1] neg_hi:[0,0,1]
	v_pk_fma_f32 v[150:151], v[150:151], v[152:153], v[154:155] op_sel_hi:[1,0,1]
	v_mov_b32_e32 v201, v149
	v_mov_b32_e32 v159, v151
	v_pk_mul_f32 v[152:153], v[114:115], v[134:135]
	v_pk_mul_f32 v[154:155], v[112:113], v[132:133]
	v_pk_mul_f32 v[150:151], v[190:191], v[158:159]
	v_pk_mul_f32 v[148:149], v[176:177], v[200:201]
	v_pk_mul_f32 v[200:201], v[152:153], v[186:187] op_sel_hi:[1,0]
	v_pk_mul_f32 v[202:203], v[154:155], v[186:187] op_sel_hi:[1,0]
	v_mov_b64_e32 v[152:153], v[240:241]
	v_mov_b64_e32 v[154:155], v[242:243]
	v_mov_b64_e32 v[156:157], v[244:245]
	v_mov_b64_e32 v[158:159], v[246:247]
	v_pk_mul_f32 v[204:205], v[156:157], v[202:203] op_sel:[1,1] op_sel_hi:[0,1]
	v_pk_fma_f32 v[206:207], v[156:157], v[202:203], v[204:205] op_sel_hi:[1,0,1] neg_lo:[0,0,1] neg_hi:[0,0,1]
	v_pk_fma_f32 v[156:157], v[156:157], v[202:203], v[204:205] op_sel_hi:[1,0,1]
	v_pk_mul_f32 v[202:203], v[158:159], v[200:201] op_sel:[1,1] op_sel_hi:[0,1]
	v_pk_fma_f32 v[204:205], v[158:159], v[200:201], v[202:203] op_sel_hi:[1,0,1] neg_lo:[0,0,1] neg_hi:[0,0,1]
	v_pk_fma_f32 v[158:159], v[158:159], v[200:201], v[202:203] op_sel_hi:[1,0,1]
	v_pk_mul_f32 v[200:201], v[86:87], v[130:131]
	v_pk_mul_f32 v[202:203], v[84:85], v[128:129]
	v_pk_mul_f32 v[200:201], v[200:201], v[186:187] op_sel_hi:[1,0]
	v_pk_mul_f32 v[186:187], v[202:203], v[186:187] op_sel_hi:[1,0]
	v_mov_b32_e32 v205, v159
	v_pk_mul_f32 v[202:203], v[152:153], v[186:187] op_sel:[1,1] op_sel_hi:[0,1]
	v_pk_mul_f32 v[158:159], v[190:191], v[204:205]
	v_pk_fma_f32 v[204:205], v[152:153], v[186:187], v[202:203] op_sel_hi:[1,0,1] neg_lo:[0,0,1] neg_hi:[0,0,1]
	v_pk_fma_f32 v[152:153], v[152:153], v[186:187], v[202:203] op_sel_hi:[1,0,1]
	v_pk_mul_f32 v[186:187], v[154:155], v[200:201] op_sel:[1,1] op_sel_hi:[0,1]
	v_pk_fma_f32 v[202:203], v[154:155], v[200:201], v[186:187] op_sel_hi:[1,0,1] neg_lo:[0,0,1] neg_hi:[0,0,1]
	v_pk_fma_f32 v[154:155], v[154:155], v[200:201], v[186:187] op_sel_hi:[1,0,1]
	v_mov_b32_e32 v207, v157
	v_mov_b32_e32 v203, v155
	v_mov_b32_e32 v205, v153
	v_pk_mul_f32 v[156:157], v[176:177], v[206:207]
	v_pk_mul_f32 v[154:155], v[190:191], v[202:203]
	v_pk_mul_f32 v[152:153], v[176:177], v[204:205]
; __device__ __forceinline__ unsigned cvt_pk_bf16(float lo, float hi) { f32x2_c v = {lo, hi}; bf16x2_c b = __builtin_convertvector(v, bf16x2_c); return __builtin_bit_cast(unsigned, b); }
;     __device__ __forceinline__ void operator()(const f32x4 (&acc)[2][2][4][2], const Unit& u, int wr, int wc, int fr, int fq) const {
;     ...
;                 for (int m = 0; m < 4; ++m) { const int row = row0 + ai * HALF + m * 16; bf16_t* rowp = PROJ + (size_t)row * PP + pn * 256 + 64 * wc + 8 * fq;
;                     f32x4 v[2][2];
; #pragma unroll
;                     for (int bj = 0; bj < 2; ++bj)
; #pragma unroll
;                         for (int n = 0; n < 2; ++n) v[bj][n] = acc[ai][bj][m][n];
;                     if (nrm) {
;                         float ss = 0.f;
; #pragma unroll
;                         for (int bj = 0; bj < 2; ++bj)
; #pragma unroll
;                             for (int n = 0; n < 2; ++n) ss += v[bj][n][0] * v[bj][n][0] + v[bj][n][1] * v[bj][n][1] + v[bj][n][2] * v[bj][n][2] + v[bj][n][3] * v[bj][n][3];
;                         ss += __shfl_xor(ss, 16); ss += __shfl_xor(ss, 32);
;                         const float rinv = __builtin_amdgcn_rsqf(ss * (1.f / 64.f) + EPS);
; #pragma unroll
;                         for (int bj = 0; bj < 2; ++bj)
; #pragma unroll
;                             for (int n = 0; n < 2; ++n) { const f32x4 x = v[bj][n] * wv[bj][n] * rinv; const f32x4 cs = *(const f32x4*)(CS + ((size_t)row * 32 + 16 * bj + 4 * fq + 2 * n) * 2);
;                                 f32x4 o; o[0] = x[0] * cs[0] - x[1] * cs[1]; o[1] = x[0] * cs[1] + x[1] * cs[0]; o[2] = x[2] * cs[2] - x[3] * cs[3]; o[3] = x[2] * cs[3] + x[3] * cs[2]; v[bj][n] = o * sc; }
;                     }
; #pragma unroll
;                     for (int bj = 0; bj < 2; ++bj) { u32x4 w; w.x = cvt_pk_bf16(v[bj][0][0], v[bj][0][1]); w.y = cvt_pk_bf16(v[bj][0][2], v[bj][0][3]); w.z = cvt_pk_bf16(v[bj][1][0], v[bj][1][1]); w.w = cvt_pk_bf16(v[bj][1][2], v[bj][1][3]);
;                         *(u32x4*)(rowp + 32 * bj) = w; } }
.LBB0_275:
	v_mov_b64_e32 v[186:187], s[24:25]
	s_lshl_b32 s7, s16, 8
	v_mad_i64_i32 v[184:185], s[56:57], v184, s64, v[186:187]
	s_lshl_b32 s56, s7, 1
	s_mov_b32 s57, s79
	v_lshl_add_u64 v[184:185], v[184:185], 0, s[56:57]
	v_lshl_add_u64 v[184:185], v[184:185], 0, s[78:79]
	v_lshl_add_u64 v[184:185], v[178:179], 1, v[184:185]
	v_cvt_pk_bf16_f32 v144, v144, v145
	v_cvt_pk_bf16_f32 v145, v146, v147
	v_cvt_pk_bf16_f32 v146, v148, v149
	v_cvt_pk_bf16_f32 v147, v150, v151
	global_store_dwordx4 v[184:185], v[144:147], off
	v_mov_b64_e32 v[150:151], v[74:75]
	s_and_b64 vcc, exec, s[4:5]
	v_cvt_pk_bf16_f32 v144, v156, v157
	v_cvt_pk_bf16_f32 v145, v158, v159
	v_cvt_pk_bf16_f32 v146, v152, v153
	v_cvt_pk_bf16_f32 v147, v154, v155
	global_store_dwordx4 v[184:185], v[144:147], off offset:64
	v_add_u32_e32 v184, 32, v180
	v_mov_b64_e32 v[154:155], v[78:79]
	v_mov_b64_e32 v[158:159], v[106:107]
	v_mov_b64_e32 v[146:147], v[110:111]
	v_ashrrev_i32_e32 v185, 31, v184
	v_mov_b64_e32 v[152:153], v[76:77]
	v_mov_b64_e32 v[156:157], v[104:105]
	v_mov_b64_e32 v[148:149], v[72:73]
	v_mov_b64_e32 v[144:145], v[108:109]
	s_cbranch_vccnz .LBB0_277
	v_mov_b32_e32 v146, v109
	v_mov_b32_e32 v147, v73
	v_mov_b32_e32 v144, v108
	v_mov_b32_e32 v145, v72
	v_pk_mul_f32 v[146:147], v[146:147], v[146:147]
	v_mov_b32_e32 v148, v105
	v_pk_fma_f32 v[144:145], v[144:145], v[144:145], v[146:147]
	v_mov_b32_e32 v146, v110
	v_mov_b32_e32 v147, v74
	v_pk_fma_f32 v[144:145], v[146:147], v[146:147], v[144:145]
	v_mov_b32_e32 v146, v111
	v_mov_b32_e32 v147, v75
	v_mov_b32_e32 v149, v77
	v_pk_fma_f32 v[144:145], v[146:147], v[146:147], v[144:145]
	v_mov_b32_e32 v146, v104
	v_mov_b32_e32 v147, v76
	v_pk_mul_f32 v[148:149], v[148:149], v[148:149]
	v_add_f32_e32 v144, v144, v145
	v_pk_fma_f32 v[146:147], v[146:147], v[146:147], v[148:149]
	v_mov_b32_e32 v148, v106
	v_mov_b32_e32 v149, v78
	v_pk_fma_f32 v[146:147], v[148:149], v[148:149], v[146:147]
	v_mov_b32_e32 v148, v107
	v_mov_b32_e32 v149, v79
	v_pk_fma_f32 v[146:147], v[148:149], v[148:149], v[146:147]
	v_mov_b32_e32 v190, v176
	v_add_f32_e32 v144, v144, v146
	v_add_f32_e32 v144, v144, v147
	v_mov_b32_e32 v145, v144
	s_nop 1
	v_permlane16_swap_b32_e32 v144, v145
	v_pk_mul_f32 v[146:147], v[108:109], v[140:141]
	v_mov_b32_e32 v191, v176
	s_waitcnt lgkmcnt(0)
	v_add_f32_e32 v144, v144, v145
	v_mov_b32_e32 v145, v144
	s_nop 1
	v_permlane32_swap_b32_e32 v144, v145
	s_waitcnt lgkmcnt(0)
	v_add_f32_e32 v144, v144, v145
	v_fmamk_f32 v144, v144, 0x3c800000, v253
	v_rsq_f32_e32 v186, v144
	v_pk_mul_f32 v[144:145], v[110:111], v[142:143]
	v_pk_mul_f32 v[154:155], v[146:147], v[186:187] op_sel_hi:[1,0]
	v_pk_mul_f32 v[152:153], v[144:145], v[186:187] op_sel_hi:[1,0]
	v_lshlrev_b64 v[144:145], 8, v[184:185]
	v_lshl_add_u64 v[144:145], s[22:23], 0, v[144:145]
	v_lshl_add_u64 v[156:157], v[182:183], 3, v[144:145]
	global_load_dwordx4 v[148:151], v[156:157], off offset:16
	global_load_dwordx4 v[144:147], v[156:157], off
	global_load_dwordx4 v[240:243], v[156:157], off offset:144
	global_load_dwordx4 v[244:247], v[156:157], off offset:128
	s_waitcnt vmcnt(0)
	v_pk_mul_f32 v[158:159], v[144:145], v[154:155] op_sel:[1,1] op_sel_hi:[0,1]
	v_pk_fma_f32 v[200:201], v[144:145], v[154:155], v[158:159] op_sel_hi:[1,0,1] neg_lo:[0,0,1] neg_hi:[0,0,1]
	v_pk_fma_f32 v[144:145], v[144:145], v[154:155], v[158:159] op_sel_hi:[1,0,1]
	v_pk_mul_f32 v[154:155], v[146:147], v[152:153] op_sel:[1,1] op_sel_hi:[0,1]
	v_pk_fma_f32 v[158:159], v[146:147], v[152:153], v[154:155] op_sel_hi:[1,0,1] neg_lo:[0,0,1] neg_hi:[0,0,1]
	v_pk_fma_f32 v[146:147], v[146:147], v[152:153], v[154:155] op_sel_hi:[1,0,1]
	v_pk_mul_f32 v[154:155], v[72:73], v[136:137]
	v_mov_b32_e32 v159, v147
	v_pk_mul_f32 v[152:153], v[74:75], v[138:139]
	v_pk_mul_f32 v[154:155], v[154:155], v[186:187] op_sel_hi:[1,0]
	v_pk_mul_f32 v[146:147], v[190:191], v[158:159]
	v_mov_b32_e32 v201, v145
	v_pk_mul_f32 v[152:153], v[152:153], v[186:187] op_sel_hi:[1,0]
	v_pk_mul_f32 v[158:159], v[148:149], v[154:155] op_sel:[1,1] op_sel_hi:[0,1]
	v_pk_mul_f32 v[144:145], v[176:177], v[200:201]
	v_pk_fma_f32 v[200:201], v[148:149], v[154:155], v[158:159] op_sel_hi:[1,0,1] neg_lo:[0,0,1] neg_hi:[0,0,1]
	v_pk_fma_f32 v[148:149], v[148:149], v[154:155], v[158:159] op_sel_hi:[1,0,1]
	v_pk_mul_f32 v[154:155], v[150:151], v[152:153] op_sel:[1,1] op_sel_hi:[0,1]
	v_pk_fma_f32 v[158:159], v[150:151], v[152:153], v[154:155] op_sel_hi:[1,0,1] neg_lo:[0,0,1] neg_hi:[0,0,1]
	v_pk_fma_f32 v[150:151], v[150:151], v[152:153], v[154:155] op_sel_hi:[1,0,1]
	v_mov_b32_e32 v201, v149
	v_mov_b32_e32 v159, v151
	v_pk_mul_f32 v[152:153], v[106:107], v[134:135]
	v_pk_mul_f32 v[154:155], v[104:105], v[132:133]
	v_pk_mul_f32 v[150:151], v[190:191], v[158:159]
	v_pk_mul_f32 v[148:149], v[176:177], v[200:201]
	v_pk_mul_f32 v[200:201], v[152:153], v[186:187] op_sel_hi:[1,0]
	v_pk_mul_f32 v[202:203], v[154:155], v[186:187] op_sel_hi:[1,0]
	v_mov_b64_e32 v[152:153], v[240:241]
	v_mov_b64_e32 v[154:155], v[242:243]
	v_mov_b64_e32 v[156:157], v[244:245]
	v_mov_b64_e32 v[158:159], v[246:247]
	v_pk_mul_f32 v[204:205], v[156:157], v[202:203] op_sel:[1,1] op_sel_hi:[0,1]
	v_pk_fma_f32 v[206:207], v[156:157], v[202:203], v[204:205] op_sel_hi:[1,0,1] neg_lo:[0,0,1] neg_hi:[0,0,1]
	v_pk_fma_f32 v[156:157], v[156:157], v[202:203], v[204:205] op_sel_hi:[1,0,1]
	v_pk_mul_f32 v[202:203], v[158:159], v[200:201] op_sel:[1,1] op_sel_hi:[0,1]
	v_pk_fma_f32 v[204:205], v[158:159], v[200:201], v[202:203] op_sel_hi:[1,0,1] neg_lo:[0,0,1] neg_hi:[0,0,1]
	v_pk_fma_f32 v[158:159], v[158:159], v[200:201], v[202:203] op_sel_hi:[1,0,1]
	v_pk_mul_f32 v[200:201], v[78:79], v[130:131]
	v_pk_mul_f32 v[202:203], v[76:77], v[128:129]
	v_pk_mul_f32 v[200:201], v[200:201], v[186:187] op_sel_hi:[1,0]
	v_pk_mul_f32 v[186:187], v[202:203], v[186:187] op_sel_hi:[1,0]
	v_mov_b32_e32 v205, v159
	v_pk_mul_f32 v[202:203], v[152:153], v[186:187] op_sel:[1,1] op_sel_hi:[0,1]
	v_pk_mul_f32 v[158:159], v[190:191], v[204:205]
	v_pk_fma_f32 v[204:205], v[152:153], v[186:187], v[202:203] op_sel_hi:[1,0,1] neg_lo:[0,0,1] neg_hi:[0,0,1]
	v_pk_fma_f32 v[152:153], v[152:153], v[186:187], v[202:203] op_sel_hi:[1,0,1]
	v_pk_mul_f32 v[186:187], v[154:155], v[200:201] op_sel:[1,1] op_sel_hi:[0,1]
	v_pk_fma_f32 v[202:203], v[154:155], v[200:201], v[186:187] op_sel_hi:[1,0,1] neg_lo:[0,0,1] neg_hi:[0,0,1]
	v_pk_fma_f32 v[154:155], v[154:155], v[200:201], v[186:187] op_sel_hi:[1,0,1]
	v_mov_b32_e32 v207, v157
	v_mov_b32_e32 v203, v155
	v_mov_b32_e32 v205, v153
	v_pk_mul_f32 v[156:157], v[176:177], v[206:207]
	v_pk_mul_f32 v[154:155], v[190:191], v[202:203]
	v_pk_mul_f32 v[152:153], v[176:177], v[204:205]
; __device__ __forceinline__ unsigned cvt_pk_bf16(float lo, float hi) { f32x2_c v = {lo, hi}; bf16x2_c b = __builtin_convertvector(v, bf16x2_c); return __builtin_bit_cast(unsigned, b); }
;     __device__ __forceinline__ void operator()(const f32x4 (&acc)[2][2][4][2], const Unit& u, int wr, int wc, int fr, int fq) const {
;     ...
;                 for (int m = 0; m < 4; ++m) { const int row = row0 + ai * HALF + m * 16; bf16_t* rowp = PROJ + (size_t)row * PP + pn * 256 + 64 * wc + 8 * fq;
;                     f32x4 v[2][2];
; #pragma unroll
;                     for (int bj = 0; bj < 2; ++bj)
; #pragma unroll
;                         for (int n = 0; n < 2; ++n) v[bj][n] = acc[ai][bj][m][n];
;                     if (nrm) {
;                         float ss = 0.f;
; #pragma unroll
;                         for (int bj = 0; bj < 2; ++bj)
; #pragma unroll
;                             for (int n = 0; n < 2; ++n) ss += v[bj][n][0] * v[bj][n][0] + v[bj][n][1] * v[bj][n][1] + v[bj][n][2] * v[bj][n][2] + v[bj][n][3] * v[bj][n][3];
;                         ss += __shfl_xor(ss, 16); ss += __shfl_xor(ss, 32);
;                         const float rinv = __builtin_amdgcn_rsqf(ss * (1.f / 64.f) + EPS);
; #pragma unroll
;                         for (int bj = 0; bj < 2; ++bj)
; #pragma unroll
;                             for (int n = 0; n < 2; ++n) { const f32x4 x = v[bj][n] * wv[bj][n] * rinv; const f32x4 cs = *(const f32x4*)(CS + ((size_t)row * 32 + 16 * bj + 4 * fq + 2 * n) * 2);
;                                 f32x4 o; o[0] = x[0] * cs[0] - x[1] * cs[1]; o[1] = x[0] * cs[1] + x[1] * cs[0]; o[2] = x[2] * cs[2] - x[3] * cs[3]; o[3] = x[2] * cs[3] + x[3] * cs[2]; v[bj][n] = o * sc; }
;                     }
; #pragma unroll
;                     for (int bj = 0; bj < 2; ++bj) { u32x4 w; w.x = cvt_pk_bf16(v[bj][0][0], v[bj][0][1]); w.y = cvt_pk_bf16(v[bj][0][2], v[bj][0][3]); w.z = cvt_pk_bf16(v[bj][1][0], v[bj][1][1]); w.w = cvt_pk_bf16(v[bj][1][2], v[bj][1][3]);
;                         *(u32x4*)(rowp + 32 * bj) = w; } }
.LBB0_277:
	v_mov_b64_e32 v[186:187], s[24:25]
	v_mad_i64_i32 v[184:185], s[62:63], v184, s64, v[186:187]
	v_lshl_add_u64 v[184:185], v[184:185], 0, s[56:57]
	v_lshl_add_u64 v[184:185], v[184:185], 0, s[78:79]
	v_lshl_add_u64 v[184:185], v[178:179], 1, v[184:185]
	v_cvt_pk_bf16_f32 v144, v144, v145
	v_cvt_pk_bf16_f32 v145, v146, v147
	v_cvt_pk_bf16_f32 v146, v148, v149
	v_cvt_pk_bf16_f32 v147, v150, v151
	global_store_dwordx4 v[184:185], v[144:147], off
	v_mov_b64_e32 v[150:151], v[66:67]
	s_and_b64 vcc, exec, s[4:5]
	v_cvt_pk_bf16_f32 v144, v156, v157
	v_cvt_pk_bf16_f32 v145, v158, v159
	v_cvt_pk_bf16_f32 v146, v152, v153
	v_cvt_pk_bf16_f32 v147, v154, v155
	global_store_dwordx4 v[184:185], v[144:147], off offset:64
	v_add_u32_e32 v184, 48, v180
	v_mov_b64_e32 v[154:155], v[70:71]
	v_mov_b64_e32 v[158:159], v[94:95]
	v_mov_b64_e32 v[146:147], v[102:103]
	v_ashrrev_i32_e32 v185, 31, v184
	v_mov_b64_e32 v[152:153], v[68:69]
	v_mov_b64_e32 v[156:157], v[92:93]
	v_mov_b64_e32 v[148:149], v[64:65]
	v_mov_b64_e32 v[144:145], v[100:101]
	s_cbranch_vccnz .LBB0_279
	v_mov_b32_e32 v146, v101
	v_mov_b32_e32 v147, v65
	v_mov_b32_e32 v144, v100
	v_mov_b32_e32 v145, v64
	v_pk_mul_f32 v[146:147], v[146:147], v[146:147]
	v_mov_b32_e32 v148, v93
	v_pk_fma_f32 v[144:145], v[144:145], v[144:145], v[146:147]
	v_mov_b32_e32 v146, v102
	v_mov_b32_e32 v147, v66
	v_pk_fma_f32 v[144:145], v[146:147], v[146:147], v[144:145]
	v_mov_b32_e32 v146, v103
	v_mov_b32_e32 v147, v67
	v_mov_b32_e32 v149, v69
	v_pk_fma_f32 v[144:145], v[146:147], v[146:147], v[144:145]
	v_mov_b32_e32 v146, v92
	v_mov_b32_e32 v147, v68
	v_pk_mul_f32 v[148:149], v[148:149], v[148:149]
	v_add_f32_e32 v144, v144, v145
	v_pk_fma_f32 v[146:147], v[146:147], v[146:147], v[148:149]
	v_mov_b32_e32 v148, v94
	v_mov_b32_e32 v149, v70
	v_pk_fma_f32 v[146:147], v[148:149], v[148:149], v[146:147]
	v_mov_b32_e32 v148, v95
	v_mov_b32_e32 v149, v71
	v_pk_fma_f32 v[146:147], v[148:149], v[148:149], v[146:147]
	v_mov_b32_e32 v190, v176
	v_add_f32_e32 v144, v144, v146
	v_add_f32_e32 v144, v144, v147
	v_mov_b32_e32 v145, v144
	s_nop 1
	v_permlane16_swap_b32_e32 v144, v145
	v_pk_mul_f32 v[146:147], v[100:101], v[140:141]
	v_mov_b32_e32 v191, v176
	s_waitcnt lgkmcnt(0)
	v_add_f32_e32 v144, v144, v145
	v_mov_b32_e32 v145, v144
	s_nop 1
	v_permlane32_swap_b32_e32 v144, v145
	s_waitcnt lgkmcnt(0)
	v_add_f32_e32 v144, v144, v145
	v_fmamk_f32 v144, v144, 0x3c800000, v253
	v_rsq_f32_e32 v186, v144
	v_pk_mul_f32 v[144:145], v[102:103], v[142:143]
	v_pk_mul_f32 v[154:155], v[146:147], v[186:187] op_sel_hi:[1,0]
	v_pk_mul_f32 v[152:153], v[144:145], v[186:187] op_sel_hi:[1,0]
	v_lshlrev_b64 v[144:145], 8, v[184:185]
	v_lshl_add_u64 v[144:145], s[22:23], 0, v[144:145]
	v_lshl_add_u64 v[156:157], v[182:183], 3, v[144:145]
	global_load_dwordx4 v[148:151], v[156:157], off offset:16
	global_load_dwordx4 v[144:147], v[156:157], off
	global_load_dwordx4 v[240:243], v[156:157], off offset:144
	global_load_dwordx4 v[244:247], v[156:157], off offset:128
	s_waitcnt vmcnt(0)
	v_pk_mul_f32 v[158:159], v[144:145], v[154:155] op_sel:[1,1] op_sel_hi:[0,1]
	v_pk_fma_f32 v[200:201], v[144:145], v[154:155], v[158:159] op_sel_hi:[1,0,1] neg_lo:[0,0,1] neg_hi:[0,0,1]
	v_pk_fma_f32 v[144:145], v[144:145], v[154:155], v[158:159] op_sel_hi:[1,0,1]
	v_pk_mul_f32 v[154:155], v[146:147], v[152:153] op_sel:[1,1] op_sel_hi:[0,1]
	v_pk_fma_f32 v[158:159], v[146:147], v[152:153], v[154:155] op_sel_hi:[1,0,1] neg_lo:[0,0,1] neg_hi:[0,0,1]
	v_pk_fma_f32 v[146:147], v[146:147], v[152:153], v[154:155] op_sel_hi:[1,0,1]
	v_pk_mul_f32 v[154:155], v[64:65], v[136:137]
	v_mov_b32_e32 v159, v147
	v_pk_mul_f32 v[152:153], v[66:67], v[138:139]
	v_pk_mul_f32 v[154:155], v[154:155], v[186:187] op_sel_hi:[1,0]
	v_pk_mul_f32 v[146:147], v[190:191], v[158:159]
	v_mov_b32_e32 v201, v145
	v_pk_mul_f32 v[152:153], v[152:153], v[186:187] op_sel_hi:[1,0]
	v_pk_mul_f32 v[158:159], v[148:149], v[154:155] op_sel:[1,1] op_sel_hi:[0,1]
	v_pk_mul_f32 v[144:145], v[176:177], v[200:201]
	v_pk_fma_f32 v[200:201], v[148:149], v[154:155], v[158:159] op_sel_hi:[1,0,1] neg_lo:[0,0,1] neg_hi:[0,0,1]
	v_pk_fma_f32 v[148:149], v[148:149], v[154:155], v[158:159] op_sel_hi:[1,0,1]
	v_pk_mul_f32 v[154:155], v[150:151], v[152:153] op_sel:[1,1] op_sel_hi:[0,1]
	v_pk_fma_f32 v[158:159], v[150:151], v[152:153], v[154:155] op_sel_hi:[1,0,1] neg_lo:[0,0,1] neg_hi:[0,0,1]
	v_pk_fma_f32 v[150:151], v[150:151], v[152:153], v[154:155] op_sel_hi:[1,0,1]
	v_mov_b32_e32 v201, v149
	v_mov_b32_e32 v159, v151
	v_pk_mul_f32 v[152:153], v[94:95], v[134:135]
	v_pk_mul_f32 v[154:155], v[92:93], v[132:133]
	v_pk_mul_f32 v[150:151], v[190:191], v[158:159]
	v_pk_mul_f32 v[148:149], v[176:177], v[200:201]
	v_pk_mul_f32 v[200:201], v[152:153], v[186:187] op_sel_hi:[1,0]
	v_pk_mul_f32 v[202:203], v[154:155], v[186:187] op_sel_hi:[1,0]
	v_mov_b64_e32 v[152:153], v[240:241]
	v_mov_b64_e32 v[154:155], v[242:243]
	v_mov_b64_e32 v[156:157], v[244:245]
	v_mov_b64_e32 v[158:159], v[246:247]
	v_pk_mul_f32 v[204:205], v[156:157], v[202:203] op_sel:[1,1] op_sel_hi:[0,1]
	v_pk_fma_f32 v[206:207], v[156:157], v[202:203], v[204:205] op_sel_hi:[1,0,1] neg_lo:[0,0,1] neg_hi:[0,0,1]
	v_pk_fma_f32 v[156:157], v[156:157], v[202:203], v[204:205] op_sel_hi:[1,0,1]
	v_pk_mul_f32 v[202:203], v[158:159], v[200:201] op_sel:[1,1] op_sel_hi:[0,1]
	v_pk_fma_f32 v[204:205], v[158:159], v[200:201], v[202:203] op_sel_hi:[1,0,1] neg_lo:[0,0,1] neg_hi:[0,0,1]
	v_pk_fma_f32 v[158:159], v[158:159], v[200:201], v[202:203] op_sel_hi:[1,0,1]
	v_pk_mul_f32 v[200:201], v[70:71], v[130:131]
	v_pk_mul_f32 v[202:203], v[68:69], v[128:129]
	v_pk_mul_f32 v[200:201], v[200:201], v[186:187] op_sel_hi:[1,0]
	v_pk_mul_f32 v[186:187], v[202:203], v[186:187] op_sel_hi:[1,0]
	v_mov_b32_e32 v205, v159
	v_pk_mul_f32 v[202:203], v[152:153], v[186:187] op_sel:[1,1] op_sel_hi:[0,1]
	v_pk_mul_f32 v[158:159], v[190:191], v[204:205]
	v_pk_fma_f32 v[204:205], v[152:153], v[186:187], v[202:203] op_sel_hi:[1,0,1] neg_lo:[0,0,1] neg_hi:[0,0,1]
	v_pk_fma_f32 v[152:153], v[152:153], v[186:187], v[202:203] op_sel_hi:[1,0,1]
	v_pk_mul_f32 v[186:187], v[154:155], v[200:201] op_sel:[1,1] op_sel_hi:[0,1]
	v_pk_fma_f32 v[202:203], v[154:155], v[200:201], v[186:187] op_sel_hi:[1,0,1] neg_lo:[0,0,1] neg_hi:[0,0,1]
	v_pk_fma_f32 v[154:155], v[154:155], v[200:201], v[186:187] op_sel_hi:[1,0,1]
	v_mov_b32_e32 v207, v157
	v_mov_b32_e32 v203, v155
	v_mov_b32_e32 v205, v153
	v_pk_mul_f32 v[156:157], v[176:177], v[206:207]
	v_pk_mul_f32 v[154:155], v[190:191], v[202:203]
	v_pk_mul_f32 v[152:153], v[176:177], v[204:205]
; __device__ __forceinline__ unsigned cvt_pk_bf16(float lo, float hi) { f32x2_c v = {lo, hi}; bf16x2_c b = __builtin_convertvector(v, bf16x2_c); return __builtin_bit_cast(unsigned, b); }
;     __device__ __forceinline__ void operator()(const f32x4 (&acc)[2][2][4][2], const Unit& u, int wr, int wc, int fr, int fq) const {
;     ...
;                 for (int m = 0; m < 4; ++m) { const int row = row0 + ai * HALF + m * 16; bf16_t* rowp = PROJ + (size_t)row * PP + pn * 256 + 64 * wc + 8 * fq;
;                     f32x4 v[2][2];
; #pragma unroll
;                     for (int bj = 0; bj < 2; ++bj)
; #pragma unroll
;                         for (int n = 0; n < 2; ++n) v[bj][n] = acc[ai][bj][m][n];
;                     if (nrm) {
;                         float ss = 0.f;
; #pragma unroll
;                         for (int bj = 0; bj < 2; ++bj)
; #pragma unroll
;                             for (int n = 0; n < 2; ++n) ss += v[bj][n][0] * v[bj][n][0] + v[bj][n][1] * v[bj][n][1] + v[bj][n][2] * v[bj][n][2] + v[bj][n][3] * v[bj][n][3];
;                         ss += __shfl_xor(ss, 16); ss += __shfl_xor(ss, 32);
;                         const float rinv = __builtin_amdgcn_rsqf(ss * (1.f / 64.f) + EPS);
; #pragma unroll
;                         for (int bj = 0; bj < 2; ++bj)
; #pragma unroll
;                             for (int n = 0; n < 2; ++n) { const f32x4 x = v[bj][n] * wv[bj][n] * rinv; const f32x4 cs = *(const f32x4*)(CS + ((size_t)row * 32 + 16 * bj + 4 * fq + 2 * n) * 2);
;                                 f32x4 o; o[0] = x[0] * cs[0] - x[1] * cs[1]; o[1] = x[0] * cs[1] + x[1] * cs[0]; o[2] = x[2] * cs[2] - x[3] * cs[3]; o[3] = x[2] * cs[3] + x[3] * cs[2]; v[bj][n] = o * sc; }
;                     }
; #pragma unroll
;                     for (int bj = 0; bj < 2; ++bj) { u32x4 w; w.x = cvt_pk_bf16(v[bj][0][0], v[bj][0][1]); w.y = cvt_pk_bf16(v[bj][0][2], v[bj][0][3]); w.z = cvt_pk_bf16(v[bj][1][0], v[bj][1][1]); w.w = cvt_pk_bf16(v[bj][1][2], v[bj][1][3]);
;                         *(u32x4*)(rowp + 32 * bj) = w; } }
.LBB0_279:
	v_mov_b64_e32 v[186:187], s[24:25]
	v_mad_i64_i32 v[184:185], s[62:63], v184, s64, v[186:187]
	s_mov_b32 s57, s79
	v_lshl_add_u64 v[184:185], v[184:185], 0, s[56:57]
	v_lshl_add_u64 v[184:185], v[184:185], 0, s[78:79]
	v_lshl_add_u64 v[184:185], v[178:179], 1, v[184:185]
	v_cvt_pk_bf16_f32 v144, v144, v145
	v_cvt_pk_bf16_f32 v145, v146, v147
	v_cvt_pk_bf16_f32 v146, v148, v149
	v_cvt_pk_bf16_f32 v147, v150, v151
	global_store_dwordx4 v[184:185], v[144:147], off
	v_mov_b64_e32 v[150:151], v[38:39]
	s_and_b64 vcc, exec, s[4:5]
	v_cvt_pk_bf16_f32 v144, v156, v157
	v_cvt_pk_bf16_f32 v145, v158, v159
	v_cvt_pk_bf16_f32 v146, v152, v153
	v_cvt_pk_bf16_f32 v147, v154, v155
	global_store_dwordx4 v[184:185], v[144:147], off offset:64
	v_add_u32_e32 v184, 0x80, v180
	v_mov_b64_e32 v[154:155], v[46:47]
	v_mov_b64_e32 v[158:159], v[58:59]
	v_mov_b64_e32 v[146:147], v[62:63]
	v_ashrrev_i32_e32 v185, 31, v184
	v_mov_b64_e32 v[152:153], v[44:45]
	v_mov_b64_e32 v[156:157], v[56:57]
	v_mov_b64_e32 v[148:149], v[36:37]
	v_mov_b64_e32 v[144:145], v[60:61]
	s_cbranch_vccnz .LBB0_281
	v_mov_b32_e32 v146, v61
	v_mov_b32_e32 v147, v37
	v_mov_b32_e32 v144, v60
	v_mov_b32_e32 v145, v36
	v_pk_mul_f32 v[146:147], v[146:147], v[146:147]
	v_mov_b32_e32 v148, v57
	v_pk_fma_f32 v[144:145], v[144:145], v[144:145], v[146:147]
	v_mov_b32_e32 v146, v62
	v_mov_b32_e32 v147, v38
	v_pk_fma_f32 v[144:145], v[146:147], v[146:147], v[144:145]
	v_mov_b32_e32 v146, v63
	v_mov_b32_e32 v147, v39
	v_mov_b32_e32 v149, v45
	v_pk_fma_f32 v[144:145], v[146:147], v[146:147], v[144:145]
	v_mov_b32_e32 v146, v56
	v_mov_b32_e32 v147, v44
	v_pk_mul_f32 v[148:149], v[148:149], v[148:149]
	v_add_f32_e32 v144, v144, v145
	v_pk_fma_f32 v[146:147], v[146:147], v[146:147], v[148:149]
	v_mov_b32_e32 v148, v58
	v_mov_b32_e32 v149, v46
	v_pk_fma_f32 v[146:147], v[148:149], v[148:149], v[146:147]
	v_mov_b32_e32 v148, v59
	v_mov_b32_e32 v149, v47
	v_pk_fma_f32 v[146:147], v[148:149], v[148:149], v[146:147]
	v_mov_b32_e32 v190, v176
	v_add_f32_e32 v144, v144, v146
	v_add_f32_e32 v144, v144, v147
	v_mov_b32_e32 v145, v144
	s_nop 1
	v_permlane16_swap_b32_e32 v144, v145
	v_pk_mul_f32 v[146:147], v[60:61], v[140:141]
	v_mov_b32_e32 v191, v176
	s_waitcnt lgkmcnt(0)
	v_add_f32_e32 v144, v144, v145
	v_mov_b32_e32 v145, v144
	s_nop 1
	v_permlane32_swap_b32_e32 v144, v145
	s_waitcnt lgkmcnt(0)
	v_add_f32_e32 v144, v144, v145
	v_fmamk_f32 v144, v144, 0x3c800000, v253
	v_rsq_f32_e32 v186, v144
	v_pk_mul_f32 v[144:145], v[62:63], v[142:143]
	v_pk_mul_f32 v[154:155], v[146:147], v[186:187] op_sel_hi:[1,0]
	v_pk_mul_f32 v[152:153], v[144:145], v[186:187] op_sel_hi:[1,0]
	v_lshlrev_b64 v[144:145], 8, v[184:185]
	v_lshl_add_u64 v[144:145], s[22:23], 0, v[144:145]
	v_lshl_add_u64 v[156:157], v[182:183], 3, v[144:145]
	global_load_dwordx4 v[148:151], v[156:157], off offset:16
	global_load_dwordx4 v[144:147], v[156:157], off
	global_load_dwordx4 v[240:243], v[156:157], off offset:144
	global_load_dwordx4 v[244:247], v[156:157], off offset:128
	s_waitcnt vmcnt(0)
	v_pk_mul_f32 v[158:159], v[144:145], v[154:155] op_sel:[1,1] op_sel_hi:[0,1]
	v_pk_fma_f32 v[200:201], v[144:145], v[154:155], v[158:159] op_sel_hi:[1,0,1] neg_lo:[0,0,1] neg_hi:[0,0,1]
	v_pk_fma_f32 v[144:145], v[144:145], v[154:155], v[158:159] op_sel_hi:[1,0,1]
	v_pk_mul_f32 v[154:155], v[146:147], v[152:153] op_sel:[1,1] op_sel_hi:[0,1]
	v_pk_fma_f32 v[158:159], v[146:147], v[152:153], v[154:155] op_sel_hi:[1,0,1] neg_lo:[0,0,1] neg_hi:[0,0,1]
	v_pk_fma_f32 v[146:147], v[146:147], v[152:153], v[154:155] op_sel_hi:[1,0,1]
	v_pk_mul_f32 v[154:155], v[36:37], v[136:137]
	v_mov_b32_e32 v159, v147
	v_pk_mul_f32 v[152:153], v[38:39], v[138:139]
	v_pk_mul_f32 v[154:155], v[154:155], v[186:187] op_sel_hi:[1,0]
	v_pk_mul_f32 v[146:147], v[190:191], v[158:159]
	v_mov_b32_e32 v201, v145
	v_pk_mul_f32 v[152:153], v[152:153], v[186:187] op_sel_hi:[1,0]
	v_pk_mul_f32 v[158:159], v[148:149], v[154:155] op_sel:[1,1] op_sel_hi:[0,1]
	v_pk_mul_f32 v[144:145], v[176:177], v[200:201]
	v_pk_fma_f32 v[200:201], v[148:149], v[154:155], v[158:159] op_sel_hi:[1,0,1] neg_lo:[0,0,1] neg_hi:[0,0,1]
	v_pk_fma_f32 v[148:149], v[148:149], v[154:155], v[158:159] op_sel_hi:[1,0,1]
	v_pk_mul_f32 v[154:155], v[150:151], v[152:153] op_sel:[1,1] op_sel_hi:[0,1]
	v_pk_fma_f32 v[158:159], v[150:151], v[152:153], v[154:155] op_sel_hi:[1,0,1] neg_lo:[0,0,1] neg_hi:[0,0,1]
	v_pk_fma_f32 v[150:151], v[150:151], v[152:153], v[154:155] op_sel_hi:[1,0,1]
	v_mov_b32_e32 v201, v149
	v_mov_b32_e32 v159, v151
	v_pk_mul_f32 v[152:153], v[58:59], v[134:135]
	v_pk_mul_f32 v[154:155], v[56:57], v[132:133]
	v_pk_mul_f32 v[150:151], v[190:191], v[158:159]
	v_pk_mul_f32 v[148:149], v[176:177], v[200:201]
	v_pk_mul_f32 v[200:201], v[152:153], v[186:187] op_sel_hi:[1,0]
	v_pk_mul_f32 v[202:203], v[154:155], v[186:187] op_sel_hi:[1,0]
	v_mov_b64_e32 v[152:153], v[240:241]
	v_mov_b64_e32 v[154:155], v[242:243]
	v_mov_b64_e32 v[156:157], v[244:245]
	v_mov_b64_e32 v[158:159], v[246:247]
	v_pk_mul_f32 v[204:205], v[156:157], v[202:203] op_sel:[1,1] op_sel_hi:[0,1]
	v_pk_fma_f32 v[206:207], v[156:157], v[202:203], v[204:205] op_sel_hi:[1,0,1] neg_lo:[0,0,1] neg_hi:[0,0,1]
	v_pk_fma_f32 v[156:157], v[156:157], v[202:203], v[204:205] op_sel_hi:[1,0,1]
	v_pk_mul_f32 v[202:203], v[158:159], v[200:201] op_sel:[1,1] op_sel_hi:[0,1]
	v_pk_fma_f32 v[204:205], v[158:159], v[200:201], v[202:203] op_sel_hi:[1,0,1] neg_lo:[0,0,1] neg_hi:[0,0,1]
	v_pk_fma_f32 v[158:159], v[158:159], v[200:201], v[202:203] op_sel_hi:[1,0,1]
	v_pk_mul_f32 v[200:201], v[46:47], v[130:131]
	v_pk_mul_f32 v[202:203], v[44:45], v[128:129]
	v_pk_mul_f32 v[200:201], v[200:201], v[186:187] op_sel_hi:[1,0]
	v_pk_mul_f32 v[186:187], v[202:203], v[186:187] op_sel_hi:[1,0]
	v_mov_b32_e32 v205, v159
	v_pk_mul_f32 v[202:203], v[152:153], v[186:187] op_sel:[1,1] op_sel_hi:[0,1]
	v_pk_mul_f32 v[158:159], v[190:191], v[204:205]
	v_pk_fma_f32 v[204:205], v[152:153], v[186:187], v[202:203] op_sel_hi:[1,0,1] neg_lo:[0,0,1] neg_hi:[0,0,1]
	v_pk_fma_f32 v[152:153], v[152:153], v[186:187], v[202:203] op_sel_hi:[1,0,1]
	v_pk_mul_f32 v[186:187], v[154:155], v[200:201] op_sel:[1,1] op_sel_hi:[0,1]
	v_pk_fma_f32 v[202:203], v[154:155], v[200:201], v[186:187] op_sel_hi:[1,0,1] neg_lo:[0,0,1] neg_hi:[0,0,1]
	v_pk_fma_f32 v[154:155], v[154:155], v[200:201], v[186:187] op_sel_hi:[1,0,1]
	v_mov_b32_e32 v207, v157
	v_mov_b32_e32 v203, v155
	v_mov_b32_e32 v205, v153
	v_pk_mul_f32 v[156:157], v[176:177], v[206:207]
	v_pk_mul_f32 v[154:155], v[190:191], v[202:203]
	v_pk_mul_f32 v[152:153], v[176:177], v[204:205]
; __device__ __forceinline__ unsigned cvt_pk_bf16(float lo, float hi) { f32x2_c v = {lo, hi}; bf16x2_c b = __builtin_convertvector(v, bf16x2_c); return __builtin_bit_cast(unsigned, b); }
;     __device__ __forceinline__ void operator()(const f32x4 (&acc)[2][2][4][2], const Unit& u, int wr, int wc, int fr, int fq) const {
;     ...
;                 for (int m = 0; m < 4; ++m) { const int row = row0 + ai * HALF + m * 16; bf16_t* rowp = PROJ + (size_t)row * PP + pn * 256 + 64 * wc + 8 * fq;
;                     f32x4 v[2][2];
; #pragma unroll
;                     for (int bj = 0; bj < 2; ++bj)
; #pragma unroll
;                         for (int n = 0; n < 2; ++n) v[bj][n] = acc[ai][bj][m][n];
;                     if (nrm) {
;                         float ss = 0.f;
; #pragma unroll
;                         for (int bj = 0; bj < 2; ++bj)
; #pragma unroll
;                             for (int n = 0; n < 2; ++n) ss += v[bj][n][0] * v[bj][n][0] + v[bj][n][1] * v[bj][n][1] + v[bj][n][2] * v[bj][n][2] + v[bj][n][3] * v[bj][n][3];
;                         ss += __shfl_xor(ss, 16); ss += __shfl_xor(ss, 32);
;                         const float rinv = __builtin_amdgcn_rsqf(ss * (1.f / 64.f) + EPS);
; #pragma unroll
;                         for (int bj = 0; bj < 2; ++bj)
; #pragma unroll
;                             for (int n = 0; n < 2; ++n) { const f32x4 x = v[bj][n] * wv[bj][n] * rinv; const f32x4 cs = *(const f32x4*)(CS + ((size_t)row * 32 + 16 * bj + 4 * fq + 2 * n) * 2);
;                                 f32x4 o; o[0] = x[0] * cs[0] - x[1] * cs[1]; o[1] = x[0] * cs[1] + x[1] * cs[0]; o[2] = x[2] * cs[2] - x[3] * cs[3]; o[3] = x[2] * cs[3] + x[3] * cs[2]; v[bj][n] = o * sc; }
;                     }
; #pragma unroll
;                     for (int bj = 0; bj < 2; ++bj) { u32x4 w; w.x = cvt_pk_bf16(v[bj][0][0], v[bj][0][1]); w.y = cvt_pk_bf16(v[bj][0][2], v[bj][0][3]); w.z = cvt_pk_bf16(v[bj][1][0], v[bj][1][1]); w.w = cvt_pk_bf16(v[bj][1][2], v[bj][1][3]);
;                         *(u32x4*)(rowp + 32 * bj) = w; } }
.LBB0_281:
	v_mov_b64_e32 v[186:187], s[24:25]
	v_mad_i64_i32 v[184:185], s[62:63], v184, s64, v[186:187]
	v_lshl_add_u64 v[184:185], v[184:185], 0, s[56:57]
	v_lshl_add_u64 v[184:185], v[184:185], 0, s[78:79]
	v_lshl_add_u64 v[184:185], v[178:179], 1, v[184:185]
	v_cvt_pk_bf16_f32 v144, v144, v145
	v_cvt_pk_bf16_f32 v145, v146, v147
	v_cvt_pk_bf16_f32 v146, v148, v149
	v_cvt_pk_bf16_f32 v147, v150, v151
	global_store_dwordx4 v[184:185], v[144:147], off
	v_mov_b64_e32 v[150:151], v[26:27]
	s_and_b64 vcc, exec, s[4:5]
	v_cvt_pk_bf16_f32 v144, v156, v157
	v_cvt_pk_bf16_f32 v145, v158, v159
	v_cvt_pk_bf16_f32 v146, v152, v153
	v_cvt_pk_bf16_f32 v147, v154, v155
	global_store_dwordx4 v[184:185], v[144:147], off offset:64
	v_add_u32_e32 v184, 0x90, v180
	v_mov_b64_e32 v[154:155], v[34:35]
	v_mov_b64_e32 v[158:159], v[50:51]
	v_mov_b64_e32 v[146:147], v[54:55]
	v_ashrrev_i32_e32 v185, 31, v184
	v_mov_b64_e32 v[152:153], v[32:33]
	v_mov_b64_e32 v[156:157], v[48:49]
	v_mov_b64_e32 v[148:149], v[24:25]
	v_mov_b64_e32 v[144:145], v[52:53]
	s_cbranch_vccnz .LBB0_283
	v_mov_b32_e32 v146, v53
	v_mov_b32_e32 v147, v25
	v_mov_b32_e32 v144, v52
	v_mov_b32_e32 v145, v24
	v_pk_mul_f32 v[146:147], v[146:147], v[146:147]
	v_mov_b32_e32 v148, v49
	v_pk_fma_f32 v[144:145], v[144:145], v[144:145], v[146:147]
	v_mov_b32_e32 v146, v54
	v_mov_b32_e32 v147, v26
	v_pk_fma_f32 v[144:145], v[146:147], v[146:147], v[144:145]
	v_mov_b32_e32 v146, v55
	v_mov_b32_e32 v147, v27
	v_mov_b32_e32 v149, v33
	v_pk_fma_f32 v[144:145], v[146:147], v[146:147], v[144:145]
	v_mov_b32_e32 v146, v48
	v_mov_b32_e32 v147, v32
	v_pk_mul_f32 v[148:149], v[148:149], v[148:149]
	v_add_f32_e32 v144, v144, v145
	v_pk_fma_f32 v[146:147], v[146:147], v[146:147], v[148:149]
	v_mov_b32_e32 v148, v50
	v_mov_b32_e32 v149, v34
	v_pk_fma_f32 v[146:147], v[148:149], v[148:149], v[146:147]
	v_mov_b32_e32 v148, v51
	v_mov_b32_e32 v149, v35
	v_pk_fma_f32 v[146:147], v[148:149], v[148:149], v[146:147]
	v_mov_b32_e32 v190, v176
	v_add_f32_e32 v144, v144, v146
	v_add_f32_e32 v144, v144, v147
	v_mov_b32_e32 v145, v144
	s_nop 1
	v_permlane16_swap_b32_e32 v144, v145
	v_pk_mul_f32 v[146:147], v[52:53], v[140:141]
	v_mov_b32_e32 v191, v176
	s_waitcnt lgkmcnt(0)
	v_add_f32_e32 v144, v144, v145
	v_mov_b32_e32 v145, v144
	s_nop 1
	v_permlane32_swap_b32_e32 v144, v145
	s_waitcnt lgkmcnt(0)
	v_add_f32_e32 v144, v144, v145
	v_fmamk_f32 v144, v144, 0x3c800000, v253
	v_rsq_f32_e32 v186, v144
	v_pk_mul_f32 v[144:145], v[54:55], v[142:143]
	v_pk_mul_f32 v[154:155], v[146:147], v[186:187] op_sel_hi:[1,0]
	v_pk_mul_f32 v[152:153], v[144:145], v[186:187] op_sel_hi:[1,0]
	v_lshlrev_b64 v[144:145], 8, v[184:185]
	v_lshl_add_u64 v[144:145], s[22:23], 0, v[144:145]
	v_lshl_add_u64 v[156:157], v[182:183], 3, v[144:145]
	global_load_dwordx4 v[148:151], v[156:157], off offset:16
	global_load_dwordx4 v[144:147], v[156:157], off
	global_load_dwordx4 v[240:243], v[156:157], off offset:144
	global_load_dwordx4 v[244:247], v[156:157], off offset:128
	s_waitcnt vmcnt(0)
	v_pk_mul_f32 v[158:159], v[144:145], v[154:155] op_sel:[1,1] op_sel_hi:[0,1]
	v_pk_fma_f32 v[200:201], v[144:145], v[154:155], v[158:159] op_sel_hi:[1,0,1] neg_lo:[0,0,1] neg_hi:[0,0,1]
	v_pk_fma_f32 v[144:145], v[144:145], v[154:155], v[158:159] op_sel_hi:[1,0,1]
	v_pk_mul_f32 v[154:155], v[146:147], v[152:153] op_sel:[1,1] op_sel_hi:[0,1]
	v_pk_fma_f32 v[158:159], v[146:147], v[152:153], v[154:155] op_sel_hi:[1,0,1] neg_lo:[0,0,1] neg_hi:[0,0,1]
	v_pk_fma_f32 v[146:147], v[146:147], v[152:153], v[154:155] op_sel_hi:[1,0,1]
	v_pk_mul_f32 v[154:155], v[24:25], v[136:137]
	v_mov_b32_e32 v159, v147
	v_pk_mul_f32 v[152:153], v[26:27], v[138:139]
	v_pk_mul_f32 v[154:155], v[154:155], v[186:187] op_sel_hi:[1,0]
	v_pk_mul_f32 v[146:147], v[190:191], v[158:159]
	v_mov_b32_e32 v201, v145
	v_pk_mul_f32 v[152:153], v[152:153], v[186:187] op_sel_hi:[1,0]
	v_pk_mul_f32 v[158:159], v[148:149], v[154:155] op_sel:[1,1] op_sel_hi:[0,1]
	v_pk_mul_f32 v[144:145], v[176:177], v[200:201]
	v_pk_fma_f32 v[200:201], v[148:149], v[154:155], v[158:159] op_sel_hi:[1,0,1] neg_lo:[0,0,1] neg_hi:[0,0,1]
	v_pk_fma_f32 v[148:149], v[148:149], v[154:155], v[158:159] op_sel_hi:[1,0,1]
	v_pk_mul_f32 v[154:155], v[150:151], v[152:153] op_sel:[1,1] op_sel_hi:[0,1]
	v_pk_fma_f32 v[158:159], v[150:151], v[152:153], v[154:155] op_sel_hi:[1,0,1] neg_lo:[0,0,1] neg_hi:[0,0,1]
	v_pk_fma_f32 v[150:151], v[150:151], v[152:153], v[154:155] op_sel_hi:[1,0,1]
	v_mov_b32_e32 v201, v149
	v_mov_b32_e32 v159, v151
	v_pk_mul_f32 v[152:153], v[50:51], v[134:135]
	v_pk_mul_f32 v[154:155], v[48:49], v[132:133]
	v_pk_mul_f32 v[150:151], v[190:191], v[158:159]
	v_pk_mul_f32 v[148:149], v[176:177], v[200:201]
	v_pk_mul_f32 v[200:201], v[152:153], v[186:187] op_sel_hi:[1,0]
	v_pk_mul_f32 v[202:203], v[154:155], v[186:187] op_sel_hi:[1,0]
	v_mov_b64_e32 v[152:153], v[240:241]
	v_mov_b64_e32 v[154:155], v[242:243]
	v_mov_b64_e32 v[156:157], v[244:245]
	v_mov_b64_e32 v[158:159], v[246:247]
	v_pk_mul_f32 v[204:205], v[156:157], v[202:203] op_sel:[1,1] op_sel_hi:[0,1]
	v_pk_fma_f32 v[206:207], v[156:157], v[202:203], v[204:205] op_sel_hi:[1,0,1] neg_lo:[0,0,1] neg_hi:[0,0,1]
	v_pk_fma_f32 v[156:157], v[156:157], v[202:203], v[204:205] op_sel_hi:[1,0,1]
	v_pk_mul_f32 v[202:203], v[158:159], v[200:201] op_sel:[1,1] op_sel_hi:[0,1]
	v_pk_fma_f32 v[204:205], v[158:159], v[200:201], v[202:203] op_sel_hi:[1,0,1] neg_lo:[0,0,1] neg_hi:[0,0,1]
	v_pk_fma_f32 v[158:159], v[158:159], v[200:201], v[202:203] op_sel_hi:[1,0,1]
	v_pk_mul_f32 v[200:201], v[34:35], v[130:131]
	v_pk_mul_f32 v[202:203], v[32:33], v[128:129]
	v_pk_mul_f32 v[200:201], v[200:201], v[186:187] op_sel_hi:[1,0]
	v_pk_mul_f32 v[186:187], v[202:203], v[186:187] op_sel_hi:[1,0]
	v_mov_b32_e32 v205, v159
	v_pk_mul_f32 v[202:203], v[152:153], v[186:187] op_sel:[1,1] op_sel_hi:[0,1]
	v_pk_mul_f32 v[158:159], v[190:191], v[204:205]
	v_pk_fma_f32 v[204:205], v[152:153], v[186:187], v[202:203] op_sel_hi:[1,0,1] neg_lo:[0,0,1] neg_hi:[0,0,1]
	v_pk_fma_f32 v[152:153], v[152:153], v[186:187], v[202:203] op_sel_hi:[1,0,1]
	v_pk_mul_f32 v[186:187], v[154:155], v[200:201] op_sel:[1,1] op_sel_hi:[0,1]
	v_pk_fma_f32 v[202:203], v[154:155], v[200:201], v[186:187] op_sel_hi:[1,0,1] neg_lo:[0,0,1] neg_hi:[0,0,1]
	v_pk_fma_f32 v[154:155], v[154:155], v[200:201], v[186:187] op_sel_hi:[1,0,1]
	v_mov_b32_e32 v207, v157
	v_mov_b32_e32 v203, v155
	v_mov_b32_e32 v205, v153
	v_pk_mul_f32 v[156:157], v[176:177], v[206:207]
	v_pk_mul_f32 v[154:155], v[190:191], v[202:203]
	v_pk_mul_f32 v[152:153], v[176:177], v[204:205]
; __device__ __forceinline__ unsigned cvt_pk_bf16(float lo, float hi) { f32x2_c v = {lo, hi}; bf16x2_c b = __builtin_convertvector(v, bf16x2_c); return __builtin_bit_cast(unsigned, b); }
;     __device__ __forceinline__ void operator()(const f32x4 (&acc)[2][2][4][2], const Unit& u, int wr, int wc, int fr, int fq) const {
;     ...
;                 for (int m = 0; m < 4; ++m) { const int row = row0 + ai * HALF + m * 16; bf16_t* rowp = PROJ + (size_t)row * PP + pn * 256 + 64 * wc + 8 * fq;
;                     f32x4 v[2][2];
; #pragma unroll
;                     for (int bj = 0; bj < 2; ++bj)
; #pragma unroll
;                         for (int n = 0; n < 2; ++n) v[bj][n] = acc[ai][bj][m][n];
;                     if (nrm) {
;                         float ss = 0.f;
; #pragma unroll
;                         for (int bj = 0; bj < 2; ++bj)
; #pragma unroll
;                             for (int n = 0; n < 2; ++n) ss += v[bj][n][0] * v[bj][n][0] + v[bj][n][1] * v[bj][n][1] + v[bj][n][2] * v[bj][n][2] + v[bj][n][3] * v[bj][n][3];
;                         ss += __shfl_xor(ss, 16); ss += __shfl_xor(ss, 32);
;                         const float rinv = __builtin_amdgcn_rsqf(ss * (1.f / 64.f) + EPS);
; #pragma unroll
;                         for (int bj = 0; bj < 2; ++bj)
; #pragma unroll
;                             for (int n = 0; n < 2; ++n) { const f32x4 x = v[bj][n] * wv[bj][n] * rinv; const f32x4 cs = *(const f32x4*)(CS + ((size_t)row * 32 + 16 * bj + 4 * fq + 2 * n) * 2);
;                                 f32x4 o; o[0] = x[0] * cs[0] - x[1] * cs[1]; o[1] = x[0] * cs[1] + x[1] * cs[0]; o[2] = x[2] * cs[2] - x[3] * cs[3]; o[3] = x[2] * cs[3] + x[3] * cs[2]; v[bj][n] = o * sc; }
;                     }
; #pragma unroll
;                     for (int bj = 0; bj < 2; ++bj) { u32x4 w; w.x = cvt_pk_bf16(v[bj][0][0], v[bj][0][1]); w.y = cvt_pk_bf16(v[bj][0][2], v[bj][0][3]); w.z = cvt_pk_bf16(v[bj][1][0], v[bj][1][1]); w.w = cvt_pk_bf16(v[bj][1][2], v[bj][1][3]);
;                         *(u32x4*)(rowp + 32 * bj) = w; } }
.LBB0_283:
	v_mov_b64_e32 v[186:187], s[24:25]
	v_mad_i64_i32 v[184:185], s[62:63], v184, s64, v[186:187]
	s_mov_b32 s57, s79
	v_lshl_add_u64 v[184:185], v[184:185], 0, s[56:57]
	v_lshl_add_u64 v[184:185], v[184:185], 0, s[78:79]
	v_lshl_add_u64 v[184:185], v[178:179], 1, v[184:185]
	v_cvt_pk_bf16_f32 v144, v144, v145
	v_cvt_pk_bf16_f32 v145, v146, v147
	v_cvt_pk_bf16_f32 v146, v148, v149
	v_cvt_pk_bf16_f32 v147, v150, v151
	global_store_dwordx4 v[184:185], v[144:147], off
	v_mov_b64_e32 v[150:151], v[14:15]
	s_and_b64 vcc, exec, s[4:5]
	v_cvt_pk_bf16_f32 v144, v156, v157
	v_cvt_pk_bf16_f32 v145, v158, v159
	v_cvt_pk_bf16_f32 v146, v152, v153
	v_cvt_pk_bf16_f32 v147, v154, v155
	global_store_dwordx4 v[184:185], v[144:147], off offset:64
	v_add_u32_e32 v184, 0xa0, v180
	v_mov_b64_e32 v[154:155], v[18:19]
	v_mov_b64_e32 v[158:159], v[30:31]
	v_mov_b64_e32 v[146:147], v[42:43]
	v_ashrrev_i32_e32 v185, 31, v184
	v_mov_b64_e32 v[152:153], v[16:17]
	v_mov_b64_e32 v[156:157], v[28:29]
	v_mov_b64_e32 v[148:149], v[12:13]
	v_mov_b64_e32 v[144:145], v[40:41]
	s_cbranch_vccnz .LBB0_285
	v_mov_b32_e32 v146, v41
	v_mov_b32_e32 v147, v13
	v_mov_b32_e32 v144, v40
	v_mov_b32_e32 v145, v12
	v_pk_mul_f32 v[146:147], v[146:147], v[146:147]
	v_mov_b32_e32 v148, v29
	v_pk_fma_f32 v[144:145], v[144:145], v[144:145], v[146:147]
	v_mov_b32_e32 v146, v42
	v_mov_b32_e32 v147, v14
	v_pk_fma_f32 v[144:145], v[146:147], v[146:147], v[144:145]
	v_mov_b32_e32 v146, v43
	v_mov_b32_e32 v147, v15
	v_mov_b32_e32 v149, v17
	v_pk_fma_f32 v[144:145], v[146:147], v[146:147], v[144:145]
	v_mov_b32_e32 v146, v28
	v_mov_b32_e32 v147, v16
	v_pk_mul_f32 v[148:149], v[148:149], v[148:149]
	v_add_f32_e32 v144, v144, v145
	v_pk_fma_f32 v[146:147], v[146:147], v[146:147], v[148:149]
	v_mov_b32_e32 v148, v30
	v_mov_b32_e32 v149, v18
	v_pk_fma_f32 v[146:147], v[148:149], v[148:149], v[146:147]
	v_mov_b32_e32 v148, v31
	v_mov_b32_e32 v149, v19
	v_pk_fma_f32 v[146:147], v[148:149], v[148:149], v[146:147]
	v_mov_b32_e32 v190, v176
	v_add_f32_e32 v144, v144, v146
	v_add_f32_e32 v144, v144, v147
	v_mov_b32_e32 v145, v144
	s_nop 1
	v_permlane16_swap_b32_e32 v144, v145
	v_pk_mul_f32 v[146:147], v[40:41], v[140:141]
	v_mov_b32_e32 v191, v176
	s_waitcnt lgkmcnt(0)
	v_add_f32_e32 v144, v144, v145
	v_mov_b32_e32 v145, v144
	s_nop 1
	v_permlane32_swap_b32_e32 v144, v145
	s_waitcnt lgkmcnt(0)
	v_add_f32_e32 v144, v144, v145
	v_fmamk_f32 v144, v144, 0x3c800000, v253
	v_rsq_f32_e32 v186, v144
	v_pk_mul_f32 v[144:145], v[42:43], v[142:143]
	v_pk_mul_f32 v[154:155], v[146:147], v[186:187] op_sel_hi:[1,0]
	v_pk_mul_f32 v[152:153], v[144:145], v[186:187] op_sel_hi:[1,0]
	v_lshlrev_b64 v[144:145], 8, v[184:185]
	v_lshl_add_u64 v[144:145], s[22:23], 0, v[144:145]
	v_lshl_add_u64 v[156:157], v[182:183], 3, v[144:145]
	global_load_dwordx4 v[148:151], v[156:157], off offset:16
	global_load_dwordx4 v[144:147], v[156:157], off
	global_load_dwordx4 v[240:243], v[156:157], off offset:144
	global_load_dwordx4 v[244:247], v[156:157], off offset:128
	s_waitcnt vmcnt(0)
	v_pk_mul_f32 v[158:159], v[144:145], v[154:155] op_sel:[1,1] op_sel_hi:[0,1]
	v_pk_fma_f32 v[200:201], v[144:145], v[154:155], v[158:159] op_sel_hi:[1,0,1] neg_lo:[0,0,1] neg_hi:[0,0,1]
	v_pk_fma_f32 v[144:145], v[144:145], v[154:155], v[158:159] op_sel_hi:[1,0,1]
	v_pk_mul_f32 v[154:155], v[146:147], v[152:153] op_sel:[1,1] op_sel_hi:[0,1]
	v_pk_fma_f32 v[158:159], v[146:147], v[152:153], v[154:155] op_sel_hi:[1,0,1] neg_lo:[0,0,1] neg_hi:[0,0,1]
	v_pk_fma_f32 v[146:147], v[146:147], v[152:153], v[154:155] op_sel_hi:[1,0,1]
	v_pk_mul_f32 v[154:155], v[12:13], v[136:137]
	v_mov_b32_e32 v159, v147
	v_pk_mul_f32 v[152:153], v[14:15], v[138:139]
	v_pk_mul_f32 v[154:155], v[154:155], v[186:187] op_sel_hi:[1,0]
	v_pk_mul_f32 v[146:147], v[190:191], v[158:159]
	v_mov_b32_e32 v201, v145
	v_pk_mul_f32 v[152:153], v[152:153], v[186:187] op_sel_hi:[1,0]
	v_pk_mul_f32 v[158:159], v[148:149], v[154:155] op_sel:[1,1] op_sel_hi:[0,1]
	v_pk_mul_f32 v[144:145], v[176:177], v[200:201]
	v_pk_fma_f32 v[200:201], v[148:149], v[154:155], v[158:159] op_sel_hi:[1,0,1] neg_lo:[0,0,1] neg_hi:[0,0,1]
	v_pk_fma_f32 v[148:149], v[148:149], v[154:155], v[158:159] op_sel_hi:[1,0,1]
	v_pk_mul_f32 v[154:155], v[150:151], v[152:153] op_sel:[1,1] op_sel_hi:[0,1]
	v_pk_fma_f32 v[158:159], v[150:151], v[152:153], v[154:155] op_sel_hi:[1,0,1] neg_lo:[0,0,1] neg_hi:[0,0,1]
	v_pk_fma_f32 v[150:151], v[150:151], v[152:153], v[154:155] op_sel_hi:[1,0,1]
	v_mov_b32_e32 v201, v149
	v_mov_b32_e32 v159, v151
	v_pk_mul_f32 v[152:153], v[30:31], v[134:135]
	v_pk_mul_f32 v[154:155], v[28:29], v[132:133]
	v_pk_mul_f32 v[150:151], v[190:191], v[158:159]
	v_pk_mul_f32 v[148:149], v[176:177], v[200:201]
	v_pk_mul_f32 v[200:201], v[152:153], v[186:187] op_sel_hi:[1,0]
	v_pk_mul_f32 v[202:203], v[154:155], v[186:187] op_sel_hi:[1,0]
	v_mov_b64_e32 v[152:153], v[240:241]
	v_mov_b64_e32 v[154:155], v[242:243]
	v_mov_b64_e32 v[156:157], v[244:245]
	v_mov_b64_e32 v[158:159], v[246:247]
	v_pk_mul_f32 v[204:205], v[156:157], v[202:203] op_sel:[1,1] op_sel_hi:[0,1]
	v_pk_fma_f32 v[206:207], v[156:157], v[202:203], v[204:205] op_sel_hi:[1,0,1] neg_lo:[0,0,1] neg_hi:[0,0,1]
	v_pk_fma_f32 v[156:157], v[156:157], v[202:203], v[204:205] op_sel_hi:[1,0,1]
	v_pk_mul_f32 v[202:203], v[158:159], v[200:201] op_sel:[1,1] op_sel_hi:[0,1]
	v_pk_fma_f32 v[204:205], v[158:159], v[200:201], v[202:203] op_sel_hi:[1,0,1] neg_lo:[0,0,1] neg_hi:[0,0,1]
	v_pk_fma_f32 v[158:159], v[158:159], v[200:201], v[202:203] op_sel_hi:[1,0,1]
	v_pk_mul_f32 v[200:201], v[18:19], v[130:131]
	v_pk_mul_f32 v[202:203], v[16:17], v[128:129]
	v_pk_mul_f32 v[200:201], v[200:201], v[186:187] op_sel_hi:[1,0]
	v_pk_mul_f32 v[186:187], v[202:203], v[186:187] op_sel_hi:[1,0]
	v_mov_b32_e32 v205, v159
	v_pk_mul_f32 v[202:203], v[152:153], v[186:187] op_sel:[1,1] op_sel_hi:[0,1]
	v_pk_mul_f32 v[158:159], v[190:191], v[204:205]
	v_pk_fma_f32 v[204:205], v[152:153], v[186:187], v[202:203] op_sel_hi:[1,0,1] neg_lo:[0,0,1] neg_hi:[0,0,1]
	v_pk_fma_f32 v[152:153], v[152:153], v[186:187], v[202:203] op_sel_hi:[1,0,1]
	v_pk_mul_f32 v[186:187], v[154:155], v[200:201] op_sel:[1,1] op_sel_hi:[0,1]
	v_pk_fma_f32 v[202:203], v[154:155], v[200:201], v[186:187] op_sel_hi:[1,0,1] neg_lo:[0,0,1] neg_hi:[0,0,1]
	v_pk_fma_f32 v[154:155], v[154:155], v[200:201], v[186:187] op_sel_hi:[1,0,1]
	v_mov_b32_e32 v207, v157
	v_mov_b32_e32 v203, v155
	v_mov_b32_e32 v205, v153
	v_pk_mul_f32 v[156:157], v[176:177], v[206:207]
	v_pk_mul_f32 v[154:155], v[190:191], v[202:203]
	v_pk_mul_f32 v[152:153], v[176:177], v[204:205]
; __device__ __forceinline__ unsigned cvt_pk_bf16(float lo, float hi) { f32x2_c v = {lo, hi}; bf16x2_c b = __builtin_convertvector(v, bf16x2_c); return __builtin_bit_cast(unsigned, b); }
;     __device__ __forceinline__ void operator()(const f32x4 (&acc)[2][2][4][2], const Unit& u, int wr, int wc, int fr, int fq) const {
;     ...
;                 for (int m = 0; m < 4; ++m) { const int row = row0 + ai * HALF + m * 16; bf16_t* rowp = PROJ + (size_t)row * PP + pn * 256 + 64 * wc + 8 * fq;
;                     f32x4 v[2][2];
; #pragma unroll
;                     for (int bj = 0; bj < 2; ++bj)
; #pragma unroll
;                         for (int n = 0; n < 2; ++n) v[bj][n] = acc[ai][bj][m][n];
;                     if (nrm) {
;                         float ss = 0.f;
; #pragma unroll
;                         for (int bj = 0; bj < 2; ++bj)
; #pragma unroll
;                             for (int n = 0; n < 2; ++n) ss += v[bj][n][0] * v[bj][n][0] + v[bj][n][1] * v[bj][n][1] + v[bj][n][2] * v[bj][n][2] + v[bj][n][3] * v[bj][n][3];
;                         ss += __shfl_xor(ss, 16); ss += __shfl_xor(ss, 32);
;                         const float rinv = __builtin_amdgcn_rsqf(ss * (1.f / 64.f) + EPS);
; #pragma unroll
;                         for (int bj = 0; bj < 2; ++bj)
; #pragma unroll
;                             for (int n = 0; n < 2; ++n) { const f32x4 x = v[bj][n] * wv[bj][n] * rinv; const f32x4 cs = *(const f32x4*)(CS + ((size_t)row * 32 + 16 * bj + 4 * fq + 2 * n) * 2);
;                                 f32x4 o; o[0] = x[0] * cs[0] - x[1] * cs[1]; o[1] = x[0] * cs[1] + x[1] * cs[0]; o[2] = x[2] * cs[2] - x[3] * cs[3]; o[3] = x[2] * cs[3] + x[3] * cs[2]; v[bj][n] = o * sc; }
;                     }
; #pragma unroll
;                     for (int bj = 0; bj < 2; ++bj) { u32x4 w; w.x = cvt_pk_bf16(v[bj][0][0], v[bj][0][1]); w.y = cvt_pk_bf16(v[bj][0][2], v[bj][0][3]); w.z = cvt_pk_bf16(v[bj][1][0], v[bj][1][1]); w.w = cvt_pk_bf16(v[bj][1][2], v[bj][1][3]);
;                         *(u32x4*)(rowp + 32 * bj) = w; } }
.LBB0_285:
	v_mov_b64_e32 v[186:187], s[24:25]
	v_mad_i64_i32 v[184:185], s[62:63], v184, s64, v[186:187]
	v_lshl_add_u64 v[184:185], v[184:185], 0, s[56:57]
	v_lshl_add_u64 v[184:185], v[184:185], 0, s[78:79]
	v_lshl_add_u64 v[184:185], v[178:179], 1, v[184:185]
	v_cvt_pk_bf16_f32 v144, v144, v145
	v_cvt_pk_bf16_f32 v145, v146, v147
	v_cvt_pk_bf16_f32 v146, v148, v149
	v_cvt_pk_bf16_f32 v147, v150, v151
	global_store_dwordx4 v[184:185], v[144:147], off
	v_add_u32_e32 v180, 0xb0, v180
	v_mov_b64_e32 v[150:151], v[2:3]
	v_cvt_pk_bf16_f32 v144, v156, v157
	v_cvt_pk_bf16_f32 v145, v158, v159
	v_cvt_pk_bf16_f32 v146, v152, v153
	v_cvt_pk_bf16_f32 v147, v154, v155
	global_store_dwordx4 v[184:185], v[144:147], off offset:64
	v_mov_b64_e32 v[158:159], v[6:7]
	v_mov_b64_e32 v[154:155], v[10:11]
	v_mov_b64_e32 v[146:147], v[22:23]
	v_ashrrev_i32_e32 v181, 31, v180
	s_and_b64 vcc, exec, s[4:5]
	v_mov_b64_e32 v[156:157], v[4:5]
	v_mov_b64_e32 v[152:153], v[8:9]
	v_mov_b64_e32 v[148:149], v[0:1]
	v_mov_b64_e32 v[144:145], v[20:21]
	s_cbranch_vccnz .LBB0_287
	v_mov_b32_e32 v146, v21
	v_mov_b32_e32 v147, v1
	v_mov_b32_e32 v144, v20
	v_mov_b32_e32 v145, v0
	v_pk_mul_f32 v[146:147], v[146:147], v[146:147]
	v_mov_b32_e32 v148, v9
	v_pk_fma_f32 v[144:145], v[144:145], v[144:145], v[146:147]
	v_mov_b32_e32 v146, v22
	v_mov_b32_e32 v147, v2
	v_pk_fma_f32 v[144:145], v[146:147], v[146:147], v[144:145]
	v_mov_b32_e32 v146, v23
	v_mov_b32_e32 v147, v3
	v_mov_b32_e32 v149, v5
	v_pk_fma_f32 v[144:145], v[146:147], v[146:147], v[144:145]
	v_mov_b32_e32 v146, v8
	v_mov_b32_e32 v147, v4
	v_pk_mul_f32 v[148:149], v[148:149], v[148:149]
	v_add_f32_e32 v144, v144, v145
	v_pk_fma_f32 v[146:147], v[146:147], v[146:147], v[148:149]
	v_mov_b32_e32 v148, v10
	v_mov_b32_e32 v149, v6
	v_pk_fma_f32 v[146:147], v[148:149], v[148:149], v[146:147]
	v_mov_b32_e32 v148, v11
	v_mov_b32_e32 v149, v7
	v_pk_fma_f32 v[146:147], v[148:149], v[148:149], v[146:147]
	s_waitcnt vmcnt(0)
	v_pk_mul_f32 v[140:141], v[20:21], v[140:141]
	v_add_f32_e32 v144, v144, v146
	v_add_f32_e32 v144, v144, v147
	v_mov_b32_e32 v145, v144
	s_nop 1
	v_permlane16_swap_b32_e32 v144, v145
	v_pk_mul_f32 v[142:143], v[22:23], v[142:143]
	v_pk_mul_f32 v[136:137], v[0:1], v[136:137]
	v_pk_mul_f32 v[138:139], v[2:3], v[138:139]
	v_pk_mul_f32 v[134:135], v[10:11], v[134:135]
	s_waitcnt lgkmcnt(0)
	v_add_f32_e32 v144, v144, v145
	v_mov_b32_e32 v145, v144
	s_nop 1
	v_permlane32_swap_b32_e32 v144, v145
	v_pk_mul_f32 v[132:133], v[8:9], v[132:133]
	v_pk_mul_f32 v[128:129], v[4:5], v[128:129]
	v_pk_mul_f32 v[130:131], v[6:7], v[130:131]
	s_waitcnt lgkmcnt(0)
	v_add_f32_e32 v144, v144, v145
	v_fmamk_f32 v144, v144, 0x3c800000, v253
	v_rsq_f32_e32 v156, v144
	s_nop 0
	v_pk_mul_f32 v[146:147], v[140:141], v[156:157] op_sel_hi:[1,0]
	v_lshlrev_b64 v[140:141], 8, v[180:181]
	v_lshl_add_u64 v[140:141], s[22:23], 0, v[140:141]
	v_lshl_add_u64 v[152:153], v[182:183], 3, v[140:141]
	v_pk_mul_f32 v[144:145], v[142:143], v[156:157] op_sel_hi:[1,0]
	global_load_dwordx4 v[148:151], v[152:153], off offset:16
	global_load_dwordx4 v[140:143], v[152:153], off
	v_pk_mul_f32 v[136:137], v[136:137], v[156:157] op_sel_hi:[1,0]
	v_pk_mul_f32 v[138:139], v[138:139], v[156:157] op_sel_hi:[1,0]
	v_pk_mul_f32 v[128:129], v[128:129], v[156:157] op_sel_hi:[1,0]
	v_pk_mul_f32 v[130:131], v[130:131], v[156:157] op_sel_hi:[1,0]
	s_waitcnt vmcnt(0)
	v_pk_mul_f32 v[154:155], v[140:141], v[146:147] op_sel:[1,1] op_sel_hi:[0,1]
	v_pk_fma_f32 v[158:159], v[140:141], v[146:147], v[154:155] op_sel_hi:[1,0,1] neg_lo:[0,0,1] neg_hi:[0,0,1]
	v_pk_fma_f32 v[154:155], v[140:141], v[146:147], v[154:155] op_sel_hi:[1,0,1]
	v_pk_mul_f32 v[140:141], v[142:143], v[144:145] op_sel:[1,1] op_sel_hi:[0,1]
	v_pk_fma_f32 v[146:147], v[142:143], v[144:145], v[140:141] op_sel_hi:[1,0,1] neg_lo:[0,0,1] neg_hi:[0,0,1]
	v_pk_fma_f32 v[140:141], v[142:143], v[144:145], v[140:141] op_sel_hi:[1,0,1]
	v_pk_mul_f32 v[142:143], v[148:149], v[136:137] op_sel:[1,1] op_sel_hi:[0,1]
	v_mov_b32_e32 v159, v155
	v_pk_fma_f32 v[154:155], v[148:149], v[136:137], v[142:143] op_sel_hi:[1,0,1] neg_lo:[0,0,1] neg_hi:[0,0,1]
	v_pk_fma_f32 v[136:137], v[148:149], v[136:137], v[142:143] op_sel_hi:[1,0,1]
	v_pk_mul_f32 v[142:143], v[150:151], v[138:139] op_sel:[1,1] op_sel_hi:[0,1]
	v_pk_fma_f32 v[148:149], v[150:151], v[138:139], v[142:143] op_sel_hi:[1,0,1] neg_lo:[0,0,1] neg_hi:[0,0,1]
	v_pk_fma_f32 v[138:139], v[150:151], v[138:139], v[142:143] op_sel_hi:[1,0,1]
	v_mov_b32_e32 v147, v141
	v_mov_b32_e32 v140, v176
	v_mov_b32_e32 v141, v176
	v_mov_b32_e32 v149, v139
	v_mov_b32_e32 v155, v137
	v_pk_mul_f32 v[150:151], v[140:141], v[148:149]
	v_pk_mul_f32 v[148:149], v[176:177], v[154:155]
	v_pk_mul_f32 v[142:143], v[134:135], v[156:157] op_sel_hi:[1,0]
	v_pk_mul_f32 v[154:155], v[132:133], v[156:157] op_sel_hi:[1,0]
	global_load_dwordx4 v[132:135], v[152:153], off offset:144
	global_load_dwordx4 v[136:139], v[152:153], off offset:128
	v_pk_mul_f32 v[144:145], v[176:177], v[158:159]
	v_pk_mul_f32 v[146:147], v[140:141], v[146:147]
	s_waitcnt vmcnt(0)
	v_pk_mul_f32 v[152:153], v[136:137], v[154:155] op_sel:[1,1] op_sel_hi:[0,1]
	v_pk_fma_f32 v[158:159], v[136:137], v[154:155], v[152:153] op_sel_hi:[1,0,1] neg_lo:[0,0,1] neg_hi:[0,0,1]
	v_pk_fma_f32 v[136:137], v[136:137], v[154:155], v[152:153] op_sel_hi:[1,0,1]
	v_pk_mul_f32 v[152:153], v[138:139], v[142:143] op_sel:[1,1] op_sel_hi:[0,1]
	v_pk_fma_f32 v[154:155], v[138:139], v[142:143], v[152:153] op_sel_hi:[1,0,1] neg_lo:[0,0,1] neg_hi:[0,0,1]
	v_pk_fma_f32 v[138:139], v[138:139], v[142:143], v[152:153] op_sel_hi:[1,0,1]
	v_mov_b32_e32 v159, v137
	v_pk_mul_f32 v[136:137], v[132:133], v[128:129] op_sel:[1,1] op_sel_hi:[0,1]
	v_mov_b32_e32 v155, v139
	v_pk_fma_f32 v[138:139], v[132:133], v[128:129], v[136:137] op_sel_hi:[1,0,1] neg_lo:[0,0,1] neg_hi:[0,0,1]
	v_pk_fma_f32 v[128:129], v[132:133], v[128:129], v[136:137] op_sel_hi:[1,0,1]
	v_pk_mul_f32 v[132:133], v[134:135], v[130:131] op_sel:[1,1] op_sel_hi:[0,1]
	v_pk_fma_f32 v[136:137], v[134:135], v[130:131], v[132:133] op_sel_hi:[1,0,1] neg_lo:[0,0,1] neg_hi:[0,0,1]
	v_pk_fma_f32 v[130:131], v[134:135], v[130:131], v[132:133] op_sel_hi:[1,0,1]
	v_mov_b32_e32 v139, v129
	v_mov_b32_e32 v137, v131
	v_pk_mul_f32 v[154:155], v[140:141], v[154:155]
	v_pk_mul_f32 v[152:153], v[176:177], v[158:159]
	v_pk_mul_f32 v[158:159], v[140:141], v[136:137]
	v_pk_mul_f32 v[156:157], v[176:177], v[138:139]
